# outproj GEMM k-loop rolled (3 k-steps per iteration) instead of fully unrolled: smaller instruction footprint
# speedup vs baseline: 1.0292x; 1.0026x over previous
.Lop_acqw:
	s_barrier
	s_lshr_b32 s1, s78, 2
	s_lshl_b32 s1, s1, 7
	s_lshl_b32 s2, s0, 8
	s_mul_i32 s3, s2, 0x800
	s_add_u32 s68, s18, s3
	s_addc_u32 s69, s19, 0
	s_mul_i32 s3, s1, 0x800
	s_add_u32 s70, s80, s3
	s_addc_u32 s71, s81, 0
	s_lshl_b32 s3, s2, 11
	s_lshl_b32 s12, s1, 1
	s_add_u32 s3, s3, s12
	s_add_u32 s74, s24, s3
	s_addc_u32 s75, s25, 0
	s_add_i32 s12, s0, -12
	s_lshr_b32 s12, s12, 2
	s_cmp_lt_u32 s0, 16
	s_cselect_b32 s12, 0, s12
	s_cselect_b32 s14, s52, s54
	s_cselect_b32 s15, s53, s55
	s_mul_i32 s13, s82, 5
	s_add_i32 s12, s12, s13
	s_mul_i32 s12, s12, 0x6000
	s_add_u32 s12, s12, 0x2000
	s_lshl_b32 s13, s1, 2
	s_add_u32 s12, s12, s13
	s_add_u32 s72, s30, s12
	s_addc_u32 s73, s31, 0
	s_and_b32 s12, s0, 15
	s_lshl_b32 s12, s12, 20
	s_add_u32 s12, s12, s13
	s_add_u32 s14, s14, s12
	s_addc_u32 s15, s15, 0
	s_cmp_eq_u32 s82, 0
	s_cselect_b32 s14, s14, s74
	s_cselect_b32 s15, s15, s75
	s_cselect_b32 s38, 64, 32
	s_cselect_b64 vcc, -1, 0
	s_lshl_b32 s39, s38, 1
	s_add_u32 s40, s39, s38
	v_cndmask_b32_e32 v191, v206, v210, vcc
	v_cndmask_b32_e32 v192, v207, v211, vcc
	v_cndmask_b32_e32 v193, v208, v168, vcc
	v_cndmask_b32_e32 v244, v209, v169, vcc
	s_add_u32 m0, s76, 0x0
	s_nop 0
	global_load_lds_dwordx4 v196, s[68:69]
	s_add_u32 m0, s76, 0x2000
	s_nop 0
	global_load_lds_dwordx4 v197, s[68:69]
	s_add_u32 m0, s76, 0x4000
	s_nop 0
	global_load_lds_dwordx4 v198, s[68:69]
	s_add_u32 m0, s76, 0x6000
	s_nop 0
	global_load_lds_dwordx4 v199, s[68:69]
	s_add_u32 m0, s76, 0x8000
	s_nop 0
	global_load_lds_dwordx4 v196, s[70:71]
	s_add_u32 m0, s76, 0xa000
	s_nop 0
	global_load_lds_dwordx4 v197, s[70:71]
	s_add_u32 s68, s68, 0x80
	s_addc_u32 s69, s69, 0
	s_add_u32 s70, s70, 0x80
	s_addc_u32 s71, s71, 0
	s_add_u32 m0, s76, 0xc000
	s_nop 0
	global_load_lds_dwordx4 v196, s[68:69]
	s_add_u32 m0, s76, 0xe000
	s_nop 0
	global_load_lds_dwordx4 v197, s[68:69]
	s_add_u32 m0, s76, 0x10000
	s_nop 0
	global_load_lds_dwordx4 v198, s[68:69]
	s_add_u32 m0, s76, 0x12000
	s_nop 0
	global_load_lds_dwordx4 v199, s[68:69]
	s_add_u32 m0, s76, 0x14000
	s_nop 0
	global_load_lds_dwordx4 v196, s[70:71]
	s_add_u32 m0, s76, 0x16000
	s_nop 0
	global_load_lds_dwordx4 v197, s[70:71]
	s_add_u32 s68, s68, 0x80
	s_addc_u32 s69, s69, 0
	s_add_u32 s70, s70, 0x80
	s_addc_u32 s71, s71, 0
	s_waitcnt vmcnt(6)
	s_barrier
	s_cmp_ge_u32 s76, 0x1000
	s_cbranch_scc1 .Lop_streamB
	v_add_u32_e32 v204, 0x0, v200
	v_add_u32_e32 v205, 0x0, v202
	ds_read_b128 v[130:133], v204 offset:0
	ds_read_b128 v[134:137], v204 offset:2048
	ds_read_b128 v[138:141], v204 offset:4096
	ds_read_b128 v[142:145], v204 offset:6144
	ds_read_b128 v[146:149], v205 offset:0
	ds_read_b128 v[150:153], v205 offset:2048
	ds_read_b128 v[154:157], v205 offset:4096
	ds_read_b128 v[158:161], v205 offset:6144
	v_add_u32_e32 v204, 0x0, v201
	v_add_u32_e32 v205, 0x0, v203
	ds_read_b128 v[212:215], v204 offset:0
	ds_read_b128 v[216:219], v204 offset:2048
	ds_read_b128 v[220:223], v204 offset:4096
	ds_read_b128 v[224:227], v204 offset:6144
	ds_read_b128 v[228:231], v205 offset:0
	ds_read_b128 v[232:235], v205 offset:2048
	ds_read_b128 v[236:239], v205 offset:4096
	ds_read_b128 v[240:243], v205 offset:6144
	s_add_u32 m0, s76, 0x18000
	s_nop 0
	global_load_lds_dwordx4 v196, s[68:69]
	s_add_u32 m0, s76, 0x1a000
	s_nop 0
	global_load_lds_dwordx4 v197, s[68:69]
	s_add_u32 m0, s76, 0x1c000
	s_nop 0
	global_load_lds_dwordx4 v198, s[68:69]
	s_add_u32 m0, s76, 0x1e000
	s_nop 0
	global_load_lds_dwordx4 v199, s[68:69]
	s_add_u32 m0, s76, 0x20000
	s_nop 0
	global_load_lds_dwordx4 v196, s[70:71]
	s_add_u32 m0, s76, 0x22000
	s_nop 0
	global_load_lds_dwordx4 v197, s[70:71]
	s_add_u32 s68, s68, 0x80
	s_addc_u32 s69, s69, 0
	s_add_u32 s70, s70, 0x80
	s_addc_u32 s71, s71, 0
	global_load_dwordx4 v[174:177], v190, s[72:73] offset:0
	global_load_dwordx4 v[178:181], v190, s[72:73] offset:64
	global_load_dwordx4 v[182:185], v190, s[72:73] offset:128
	global_load_dwordx4 v[186:189], v190, s[72:73] offset:192
	global_load_dwordx4 v[66:69], v191, s[14:15]
	v_add_u32_e32 v170, s38, v191
	global_load_dwordx4 v[70:73], v170, s[14:15]
	v_add_u32_e32 v170, s39, v191
	global_load_dwordx4 v[74:77], v170, s[14:15]
	s_waitcnt lgkmcnt(0)
	s_barrier
	v_mfma_f32_16x16x32_bf16 v[2:5], v[146:149], v[130:133], 0
	v_mfma_f32_16x16x32_bf16 v[6:9], v[150:153], v[130:133], 0
	v_mfma_f32_16x16x32_bf16 v[10:13], v[154:157], v[130:133], 0
	v_mfma_f32_16x16x32_bf16 v[14:17], v[158:161], v[130:133], 0
	v_mfma_f32_16x16x32_bf16 v[18:21], v[146:149], v[134:137], 0
	v_mfma_f32_16x16x32_bf16 v[22:25], v[150:153], v[134:137], 0
	v_mfma_f32_16x16x32_bf16 v[26:29], v[154:157], v[134:137], 0
	v_mfma_f32_16x16x32_bf16 v[30:33], v[158:161], v[134:137], 0
	v_mfma_f32_16x16x32_bf16 v[34:37], v[146:149], v[138:141], 0
	v_mfma_f32_16x16x32_bf16 v[38:41], v[150:153], v[138:141], 0
	v_mfma_f32_16x16x32_bf16 v[42:45], v[154:157], v[138:141], 0
	v_mfma_f32_16x16x32_bf16 v[46:49], v[158:161], v[138:141], 0
	v_mfma_f32_16x16x32_bf16 v[50:53], v[146:149], v[142:145], 0
	v_mfma_f32_16x16x32_bf16 v[54:57], v[150:153], v[142:145], 0
	v_mfma_f32_16x16x32_bf16 v[58:61], v[154:157], v[142:145], 0
	v_mfma_f32_16x16x32_bf16 v[62:65], v[158:161], v[142:145], 0
	v_mfma_f32_16x16x32_bf16 v[2:5], v[228:231], v[212:215], v[2:5]
	v_mfma_f32_16x16x32_bf16 v[6:9], v[232:235], v[212:215], v[6:9]
	v_mfma_f32_16x16x32_bf16 v[10:13], v[236:239], v[212:215], v[10:13]
	v_mfma_f32_16x16x32_bf16 v[14:17], v[240:243], v[212:215], v[14:17]
	v_mfma_f32_16x16x32_bf16 v[18:21], v[228:231], v[216:219], v[18:21]
	v_mfma_f32_16x16x32_bf16 v[22:25], v[232:235], v[216:219], v[22:25]
	v_mfma_f32_16x16x32_bf16 v[26:29], v[236:239], v[216:219], v[26:29]
	v_mfma_f32_16x16x32_bf16 v[30:33], v[240:243], v[216:219], v[30:33]
	v_mfma_f32_16x16x32_bf16 v[34:37], v[228:231], v[220:223], v[34:37]
	v_mfma_f32_16x16x32_bf16 v[38:41], v[232:235], v[220:223], v[38:41]
	v_mfma_f32_16x16x32_bf16 v[42:45], v[236:239], v[220:223], v[42:45]
	v_mfma_f32_16x16x32_bf16 v[46:49], v[240:243], v[220:223], v[46:49]
	v_mfma_f32_16x16x32_bf16 v[50:53], v[228:231], v[224:227], v[50:53]
	v_mfma_f32_16x16x32_bf16 v[54:57], v[232:235], v[224:227], v[54:57]
	v_mfma_f32_16x16x32_bf16 v[58:61], v[236:239], v[224:227], v[58:61]
	v_mfma_f32_16x16x32_bf16 v[62:65], v[240:243], v[224:227], v[62:65]
	s_waitcnt vmcnt(13)
	s_barrier
	v_add_u32_e32 v204, 0xc000, v200
	v_add_u32_e32 v205, 0xc000, v202
	ds_read_b128 v[130:133], v204 offset:0
	ds_read_b128 v[134:137], v204 offset:2048
	ds_read_b128 v[138:141], v204 offset:4096
	ds_read_b128 v[142:145], v204 offset:6144
	ds_read_b128 v[146:149], v205 offset:0
	ds_read_b128 v[150:153], v205 offset:2048
	ds_read_b128 v[154:157], v205 offset:4096
	ds_read_b128 v[158:161], v205 offset:6144
	v_add_u32_e32 v204, 0xc000, v201
	v_add_u32_e32 v205, 0xc000, v203
	ds_read_b128 v[212:215], v204 offset:0
	ds_read_b128 v[216:219], v204 offset:2048
	ds_read_b128 v[220:223], v204 offset:4096
	ds_read_b128 v[224:227], v204 offset:6144
	ds_read_b128 v[228:231], v205 offset:0
	ds_read_b128 v[232:235], v205 offset:2048
	ds_read_b128 v[236:239], v205 offset:4096
	ds_read_b128 v[240:243], v205 offset:6144
	s_add_u32 m0, s76, 0x0
	s_nop 0
	global_load_lds_dwordx4 v196, s[68:69]
	s_add_u32 m0, s76, 0x2000
	s_nop 0
	global_load_lds_dwordx4 v197, s[68:69]
	s_add_u32 m0, s76, 0x4000
	s_nop 0
	global_load_lds_dwordx4 v198, s[68:69]
	s_add_u32 m0, s76, 0x6000
	s_nop 0
	global_load_lds_dwordx4 v199, s[68:69]
	s_add_u32 m0, s76, 0x8000
	s_nop 0
	global_load_lds_dwordx4 v196, s[70:71]
	s_add_u32 m0, s76, 0xa000
	s_nop 0
	global_load_lds_dwordx4 v197, s[70:71]
	s_add_u32 s68, s68, 0x80
	s_addc_u32 s69, s69, 0
	s_add_u32 s70, s70, 0x80
	s_addc_u32 s71, s71, 0
	v_add_u32_e32 v170, s40, v191
	global_load_dwordx4 v[78:81], v170, s[14:15]
	global_load_dwordx4 v[82:85], v192, s[14:15]
	v_add_u32_e32 v170, s38, v192
	global_load_dwordx4 v[86:89], v170, s[14:15]
	v_add_u32_e32 v170, s39, v192
	global_load_dwordx4 v[90:93], v170, s[14:15]
	v_add_u32_e32 v170, s40, v192
	global_load_dwordx4 v[94:97], v170, s[14:15]
	global_load_dwordx4 v[98:101], v193, s[14:15]
	v_add_u32_e32 v170, s38, v193
	global_load_dwordx4 v[102:105], v170, s[14:15]
	s_waitcnt lgkmcnt(0)
	s_barrier
	v_mfma_f32_16x16x32_bf16 v[2:5], v[146:149], v[130:133], v[2:5]
	v_mfma_f32_16x16x32_bf16 v[6:9], v[150:153], v[130:133], v[6:9]
	v_mfma_f32_16x16x32_bf16 v[10:13], v[154:157], v[130:133], v[10:13]
	v_mfma_f32_16x16x32_bf16 v[14:17], v[158:161], v[130:133], v[14:17]
	v_mfma_f32_16x16x32_bf16 v[18:21], v[146:149], v[134:137], v[18:21]
	v_mfma_f32_16x16x32_bf16 v[22:25], v[150:153], v[134:137], v[22:25]
	v_mfma_f32_16x16x32_bf16 v[26:29], v[154:157], v[134:137], v[26:29]
	v_mfma_f32_16x16x32_bf16 v[30:33], v[158:161], v[134:137], v[30:33]
	v_mfma_f32_16x16x32_bf16 v[34:37], v[146:149], v[138:141], v[34:37]
	v_mfma_f32_16x16x32_bf16 v[38:41], v[150:153], v[138:141], v[38:41]
	v_mfma_f32_16x16x32_bf16 v[42:45], v[154:157], v[138:141], v[42:45]
	v_mfma_f32_16x16x32_bf16 v[46:49], v[158:161], v[138:141], v[46:49]
	v_mfma_f32_16x16x32_bf16 v[50:53], v[146:149], v[142:145], v[50:53]
	v_mfma_f32_16x16x32_bf16 v[54:57], v[150:153], v[142:145], v[54:57]
	v_mfma_f32_16x16x32_bf16 v[58:61], v[154:157], v[142:145], v[58:61]
	v_mfma_f32_16x16x32_bf16 v[62:65], v[158:161], v[142:145], v[62:65]
	v_mfma_f32_16x16x32_bf16 v[2:5], v[228:231], v[212:215], v[2:5]
	v_mfma_f32_16x16x32_bf16 v[6:9], v[232:235], v[212:215], v[6:9]
	v_mfma_f32_16x16x32_bf16 v[10:13], v[236:239], v[212:215], v[10:13]
	v_mfma_f32_16x16x32_bf16 v[14:17], v[240:243], v[212:215], v[14:17]
	v_mfma_f32_16x16x32_bf16 v[18:21], v[228:231], v[216:219], v[18:21]
	v_mfma_f32_16x16x32_bf16 v[22:25], v[232:235], v[216:219], v[22:25]
	v_mfma_f32_16x16x32_bf16 v[26:29], v[236:239], v[216:219], v[26:29]
	v_mfma_f32_16x16x32_bf16 v[30:33], v[240:243], v[216:219], v[30:33]
	v_mfma_f32_16x16x32_bf16 v[34:37], v[228:231], v[220:223], v[34:37]
	v_mfma_f32_16x16x32_bf16 v[38:41], v[232:235], v[220:223], v[38:41]
	v_mfma_f32_16x16x32_bf16 v[42:45], v[236:239], v[220:223], v[42:45]
	v_mfma_f32_16x16x32_bf16 v[46:49], v[240:243], v[220:223], v[46:49]
	v_mfma_f32_16x16x32_bf16 v[50:53], v[228:231], v[224:227], v[50:53]
	v_mfma_f32_16x16x32_bf16 v[54:57], v[232:235], v[224:227], v[54:57]
	v_mfma_f32_16x16x32_bf16 v[58:61], v[236:239], v[224:227], v[58:61]
	v_mfma_f32_16x16x32_bf16 v[62:65], v[240:243], v[224:227], v[62:65]
	s_waitcnt vmcnt(20)
	s_barrier
	v_add_u32_e32 v204, 0x18000, v200
	v_add_u32_e32 v205, 0x18000, v202
	ds_read_b128 v[130:133], v204 offset:0
	ds_read_b128 v[134:137], v204 offset:2048
	ds_read_b128 v[138:141], v204 offset:4096
	ds_read_b128 v[142:145], v204 offset:6144
	ds_read_b128 v[146:149], v205 offset:0
	ds_read_b128 v[150:153], v205 offset:2048
	ds_read_b128 v[154:157], v205 offset:4096
	ds_read_b128 v[158:161], v205 offset:6144
	v_add_u32_e32 v204, 0x18000, v201
	v_add_u32_e32 v205, 0x18000, v203
	ds_read_b128 v[212:215], v204 offset:0
	ds_read_b128 v[216:219], v204 offset:2048
	ds_read_b128 v[220:223], v204 offset:4096
	ds_read_b128 v[224:227], v204 offset:6144
	ds_read_b128 v[228:231], v205 offset:0
	ds_read_b128 v[232:235], v205 offset:2048
	ds_read_b128 v[236:239], v205 offset:4096
	ds_read_b128 v[240:243], v205 offset:6144
	s_add_u32 m0, s76, 0xc000
	s_nop 0
	global_load_lds_dwordx4 v196, s[68:69]
	s_add_u32 m0, s76, 0xe000
	s_nop 0
	global_load_lds_dwordx4 v197, s[68:69]
	s_add_u32 m0, s76, 0x10000
	s_nop 0
	global_load_lds_dwordx4 v198, s[68:69]
	s_add_u32 m0, s76, 0x12000
	s_nop 0
	global_load_lds_dwordx4 v199, s[68:69]
	s_add_u32 m0, s76, 0x14000
	s_nop 0
	global_load_lds_dwordx4 v196, s[70:71]
	s_add_u32 m0, s76, 0x16000
	s_nop 0
	global_load_lds_dwordx4 v197, s[70:71]
	s_add_u32 s68, s68, 0x80
	s_addc_u32 s69, s69, 0
	s_add_u32 s70, s70, 0x80
	s_addc_u32 s71, s71, 0
	v_add_u32_e32 v170, s39, v193
	global_load_dwordx4 v[106:109], v170, s[14:15]
	v_add_u32_e32 v170, s40, v193
	global_load_dwordx4 v[110:113], v170, s[14:15]
	global_load_dwordx4 v[114:117], v244, s[14:15]
	v_add_u32_e32 v170, s38, v244
	global_load_dwordx4 v[118:121], v170, s[14:15]
	v_add_u32_e32 v170, s39, v244
	global_load_dwordx4 v[122:125], v170, s[14:15]
	v_add_u32_e32 v170, s40, v244
	global_load_dwordx4 v[126:129], v170, s[14:15]
	s_waitcnt lgkmcnt(0)
	s_barrier
	v_mfma_f32_16x16x32_bf16 v[2:5], v[146:149], v[130:133], v[2:5]
	v_mfma_f32_16x16x32_bf16 v[6:9], v[150:153], v[130:133], v[6:9]
	v_mfma_f32_16x16x32_bf16 v[10:13], v[154:157], v[130:133], v[10:13]
	v_mfma_f32_16x16x32_bf16 v[14:17], v[158:161], v[130:133], v[14:17]
	v_mfma_f32_16x16x32_bf16 v[18:21], v[146:149], v[134:137], v[18:21]
	v_mfma_f32_16x16x32_bf16 v[22:25], v[150:153], v[134:137], v[22:25]
	v_mfma_f32_16x16x32_bf16 v[26:29], v[154:157], v[134:137], v[26:29]
	v_mfma_f32_16x16x32_bf16 v[30:33], v[158:161], v[134:137], v[30:33]
	v_mfma_f32_16x16x32_bf16 v[34:37], v[146:149], v[138:141], v[34:37]
	v_mfma_f32_16x16x32_bf16 v[38:41], v[150:153], v[138:141], v[38:41]
	v_mfma_f32_16x16x32_bf16 v[42:45], v[154:157], v[138:141], v[42:45]
	v_mfma_f32_16x16x32_bf16 v[46:49], v[158:161], v[138:141], v[46:49]
	v_mfma_f32_16x16x32_bf16 v[50:53], v[146:149], v[142:145], v[50:53]
	v_mfma_f32_16x16x32_bf16 v[54:57], v[150:153], v[142:145], v[54:57]
	v_mfma_f32_16x16x32_bf16 v[58:61], v[154:157], v[142:145], v[58:61]
	v_mfma_f32_16x16x32_bf16 v[62:65], v[158:161], v[142:145], v[62:65]
	v_mfma_f32_16x16x32_bf16 v[2:5], v[228:231], v[212:215], v[2:5]
	v_mfma_f32_16x16x32_bf16 v[6:9], v[232:235], v[212:215], v[6:9]
	v_mfma_f32_16x16x32_bf16 v[10:13], v[236:239], v[212:215], v[10:13]
	v_mfma_f32_16x16x32_bf16 v[14:17], v[240:243], v[212:215], v[14:17]
	v_mfma_f32_16x16x32_bf16 v[18:21], v[228:231], v[216:219], v[18:21]
	v_mfma_f32_16x16x32_bf16 v[22:25], v[232:235], v[216:219], v[22:25]
	v_mfma_f32_16x16x32_bf16 v[26:29], v[236:239], v[216:219], v[26:29]
	v_mfma_f32_16x16x32_bf16 v[30:33], v[240:243], v[216:219], v[30:33]
	v_mfma_f32_16x16x32_bf16 v[34:37], v[228:231], v[220:223], v[34:37]
	v_mfma_f32_16x16x32_bf16 v[38:41], v[232:235], v[220:223], v[38:41]
	v_mfma_f32_16x16x32_bf16 v[42:45], v[236:239], v[220:223], v[42:45]
	v_mfma_f32_16x16x32_bf16 v[46:49], v[240:243], v[220:223], v[46:49]
	v_mfma_f32_16x16x32_bf16 v[50:53], v[228:231], v[224:227], v[50:53]
	v_mfma_f32_16x16x32_bf16 v[54:57], v[232:235], v[224:227], v[54:57]
	v_mfma_f32_16x16x32_bf16 v[58:61], v[236:239], v[224:227], v[58:61]
	v_mfma_f32_16x16x32_bf16 v[62:65], v[240:243], v[224:227], v[62:65]
	s_waitcnt vmcnt(19)
	s_barrier
	v_add_u32_e32 v204, 0x0, v200
	v_add_u32_e32 v205, 0x0, v202
	ds_read_b128 v[130:133], v204 offset:0
	ds_read_b128 v[134:137], v204 offset:2048
	ds_read_b128 v[138:141], v204 offset:4096
	ds_read_b128 v[142:145], v204 offset:6144
	ds_read_b128 v[146:149], v205 offset:0
	ds_read_b128 v[150:153], v205 offset:2048
	ds_read_b128 v[154:157], v205 offset:4096
	ds_read_b128 v[158:161], v205 offset:6144
	v_add_u32_e32 v204, 0x0, v201
	v_add_u32_e32 v205, 0x0, v203
	ds_read_b128 v[212:215], v204 offset:0
	ds_read_b128 v[216:219], v204 offset:2048
	ds_read_b128 v[220:223], v204 offset:4096
	ds_read_b128 v[224:227], v204 offset:6144
	ds_read_b128 v[228:231], v205 offset:0
	ds_read_b128 v[232:235], v205 offset:2048
	ds_read_b128 v[236:239], v205 offset:4096
	ds_read_b128 v[240:243], v205 offset:6144
	s_add_u32 m0, s76, 0x18000
	s_nop 0
	global_load_lds_dwordx4 v196, s[68:69]
	s_add_u32 m0, s76, 0x1a000
	s_nop 0
	global_load_lds_dwordx4 v197, s[68:69]
	s_add_u32 m0, s76, 0x1c000
	s_nop 0
	global_load_lds_dwordx4 v198, s[68:69]
	s_add_u32 m0, s76, 0x1e000
	s_nop 0
	global_load_lds_dwordx4 v199, s[68:69]
	s_add_u32 m0, s76, 0x20000
	s_nop 0
	global_load_lds_dwordx4 v196, s[70:71]
	s_add_u32 m0, s76, 0x22000
	s_nop 0
	global_load_lds_dwordx4 v197, s[70:71]
	s_add_u32 s68, s68, 0x80
	s_addc_u32 s69, s69, 0
	s_add_u32 s70, s70, 0x80
	s_addc_u32 s71, s71, 0
	s_waitcnt lgkmcnt(0)
	s_barrier
	v_mfma_f32_16x16x32_bf16 v[2:5], v[146:149], v[130:133], v[2:5]
	v_mfma_f32_16x16x32_bf16 v[6:9], v[150:153], v[130:133], v[6:9]
	v_mfma_f32_16x16x32_bf16 v[10:13], v[154:157], v[130:133], v[10:13]
	v_mfma_f32_16x16x32_bf16 v[14:17], v[158:161], v[130:133], v[14:17]
	v_mfma_f32_16x16x32_bf16 v[18:21], v[146:149], v[134:137], v[18:21]
	v_mfma_f32_16x16x32_bf16 v[22:25], v[150:153], v[134:137], v[22:25]
	v_mfma_f32_16x16x32_bf16 v[26:29], v[154:157], v[134:137], v[26:29]
	v_mfma_f32_16x16x32_bf16 v[30:33], v[158:161], v[134:137], v[30:33]
	v_mfma_f32_16x16x32_bf16 v[34:37], v[146:149], v[138:141], v[34:37]
	v_mfma_f32_16x16x32_bf16 v[38:41], v[150:153], v[138:141], v[38:41]
	v_mfma_f32_16x16x32_bf16 v[42:45], v[154:157], v[138:141], v[42:45]
	v_mfma_f32_16x16x32_bf16 v[46:49], v[158:161], v[138:141], v[46:49]
	v_mfma_f32_16x16x32_bf16 v[50:53], v[146:149], v[142:145], v[50:53]
	v_mfma_f32_16x16x32_bf16 v[54:57], v[150:153], v[142:145], v[54:57]
	v_mfma_f32_16x16x32_bf16 v[58:61], v[154:157], v[142:145], v[58:61]
	v_mfma_f32_16x16x32_bf16 v[62:65], v[158:161], v[142:145], v[62:65]
	v_mfma_f32_16x16x32_bf16 v[2:5], v[228:231], v[212:215], v[2:5]
	v_mfma_f32_16x16x32_bf16 v[6:9], v[232:235], v[212:215], v[6:9]
	v_mfma_f32_16x16x32_bf16 v[10:13], v[236:239], v[212:215], v[10:13]
	v_mfma_f32_16x16x32_bf16 v[14:17], v[240:243], v[212:215], v[14:17]
	v_mfma_f32_16x16x32_bf16 v[18:21], v[228:231], v[216:219], v[18:21]
	v_mfma_f32_16x16x32_bf16 v[22:25], v[232:235], v[216:219], v[22:25]
	v_mfma_f32_16x16x32_bf16 v[26:29], v[236:239], v[216:219], v[26:29]
	v_mfma_f32_16x16x32_bf16 v[30:33], v[240:243], v[216:219], v[30:33]
	v_mfma_f32_16x16x32_bf16 v[34:37], v[228:231], v[220:223], v[34:37]
	v_mfma_f32_16x16x32_bf16 v[38:41], v[232:235], v[220:223], v[38:41]
	v_mfma_f32_16x16x32_bf16 v[42:45], v[236:239], v[220:223], v[42:45]
	v_mfma_f32_16x16x32_bf16 v[46:49], v[240:243], v[220:223], v[46:49]
	v_mfma_f32_16x16x32_bf16 v[50:53], v[228:231], v[224:227], v[50:53]
	v_mfma_f32_16x16x32_bf16 v[54:57], v[232:235], v[224:227], v[54:57]
	v_mfma_f32_16x16x32_bf16 v[58:61], v[236:239], v[224:227], v[58:61]
	v_mfma_f32_16x16x32_bf16 v[62:65], v[240:243], v[224:227], v[62:65]
	s_waitcnt vmcnt(12)
	s_barrier
	v_add_u32_e32 v204, 0xc000, v200
	v_add_u32_e32 v205, 0xc000, v202
	ds_read_b128 v[130:133], v204 offset:0
	ds_read_b128 v[134:137], v204 offset:2048
	ds_read_b128 v[138:141], v204 offset:4096
	ds_read_b128 v[142:145], v204 offset:6144
	ds_read_b128 v[146:149], v205 offset:0
	ds_read_b128 v[150:153], v205 offset:2048
	ds_read_b128 v[154:157], v205 offset:4096
	ds_read_b128 v[158:161], v205 offset:6144
	v_add_u32_e32 v204, 0xc000, v201
	v_add_u32_e32 v205, 0xc000, v203
	ds_read_b128 v[212:215], v204 offset:0
	ds_read_b128 v[216:219], v204 offset:2048
	ds_read_b128 v[220:223], v204 offset:4096
	ds_read_b128 v[224:227], v204 offset:6144
	ds_read_b128 v[228:231], v205 offset:0
	ds_read_b128 v[232:235], v205 offset:2048
	ds_read_b128 v[236:239], v205 offset:4096
	ds_read_b128 v[240:243], v205 offset:6144
	s_add_u32 m0, s76, 0x0
	s_nop 0
	global_load_lds_dwordx4 v196, s[68:69]
	s_add_u32 m0, s76, 0x2000
	s_nop 0
	global_load_lds_dwordx4 v197, s[68:69]
	s_add_u32 m0, s76, 0x4000
	s_nop 0
	global_load_lds_dwordx4 v198, s[68:69]
	s_add_u32 m0, s76, 0x6000
	s_nop 0
	global_load_lds_dwordx4 v199, s[68:69]
	s_add_u32 m0, s76, 0x8000
	s_nop 0
	global_load_lds_dwordx4 v196, s[70:71]
	s_add_u32 m0, s76, 0xa000
	s_nop 0
	global_load_lds_dwordx4 v197, s[70:71]
	s_add_u32 s68, s68, 0x80
	s_addc_u32 s69, s69, 0
	s_add_u32 s70, s70, 0x80
	s_addc_u32 s71, s71, 0
	s_waitcnt lgkmcnt(0)
	s_barrier
	v_mfma_f32_16x16x32_bf16 v[2:5], v[146:149], v[130:133], v[2:5]
	v_mfma_f32_16x16x32_bf16 v[6:9], v[150:153], v[130:133], v[6:9]
	v_mfma_f32_16x16x32_bf16 v[10:13], v[154:157], v[130:133], v[10:13]
	v_mfma_f32_16x16x32_bf16 v[14:17], v[158:161], v[130:133], v[14:17]
	v_mfma_f32_16x16x32_bf16 v[18:21], v[146:149], v[134:137], v[18:21]
	v_mfma_f32_16x16x32_bf16 v[22:25], v[150:153], v[134:137], v[22:25]
	v_mfma_f32_16x16x32_bf16 v[26:29], v[154:157], v[134:137], v[26:29]
	v_mfma_f32_16x16x32_bf16 v[30:33], v[158:161], v[134:137], v[30:33]
	v_mfma_f32_16x16x32_bf16 v[34:37], v[146:149], v[138:141], v[34:37]
	v_mfma_f32_16x16x32_bf16 v[38:41], v[150:153], v[138:141], v[38:41]
	v_mfma_f32_16x16x32_bf16 v[42:45], v[154:157], v[138:141], v[42:45]
	v_mfma_f32_16x16x32_bf16 v[46:49], v[158:161], v[138:141], v[46:49]
	v_mfma_f32_16x16x32_bf16 v[50:53], v[146:149], v[142:145], v[50:53]
	v_mfma_f32_16x16x32_bf16 v[54:57], v[150:153], v[142:145], v[54:57]
	v_mfma_f32_16x16x32_bf16 v[58:61], v[154:157], v[142:145], v[58:61]
	v_mfma_f32_16x16x32_bf16 v[62:65], v[158:161], v[142:145], v[62:65]
	v_mfma_f32_16x16x32_bf16 v[2:5], v[228:231], v[212:215], v[2:5]
	v_mfma_f32_16x16x32_bf16 v[6:9], v[232:235], v[212:215], v[6:9]
	v_mfma_f32_16x16x32_bf16 v[10:13], v[236:239], v[212:215], v[10:13]
	v_mfma_f32_16x16x32_bf16 v[14:17], v[240:243], v[212:215], v[14:17]
	v_mfma_f32_16x16x32_bf16 v[18:21], v[228:231], v[216:219], v[18:21]
	v_mfma_f32_16x16x32_bf16 v[22:25], v[232:235], v[216:219], v[22:25]
	v_mfma_f32_16x16x32_bf16 v[26:29], v[236:239], v[216:219], v[26:29]
	v_mfma_f32_16x16x32_bf16 v[30:33], v[240:243], v[216:219], v[30:33]
	v_mfma_f32_16x16x32_bf16 v[34:37], v[228:231], v[220:223], v[34:37]
	v_mfma_f32_16x16x32_bf16 v[38:41], v[232:235], v[220:223], v[38:41]
	v_mfma_f32_16x16x32_bf16 v[42:45], v[236:239], v[220:223], v[42:45]
	v_mfma_f32_16x16x32_bf16 v[46:49], v[240:243], v[220:223], v[46:49]
	v_mfma_f32_16x16x32_bf16 v[50:53], v[228:231], v[224:227], v[50:53]
	v_mfma_f32_16x16x32_bf16 v[54:57], v[232:235], v[224:227], v[54:57]
	v_mfma_f32_16x16x32_bf16 v[58:61], v[236:239], v[224:227], v[58:61]
	v_mfma_f32_16x16x32_bf16 v[62:65], v[240:243], v[224:227], v[62:65]
	s_waitcnt vmcnt(6)
	s_barrier
	s_mov_b32 s16, 3
.Lop_kloop1:
	v_add_u32_e32 v204, 0x18000, v200
	v_add_u32_e32 v205, 0x18000, v202
	ds_read_b128 v[130:133], v204 offset:0
	ds_read_b128 v[134:137], v204 offset:2048
	ds_read_b128 v[138:141], v204 offset:4096
	ds_read_b128 v[142:145], v204 offset:6144
	ds_read_b128 v[146:149], v205 offset:0
	ds_read_b128 v[150:153], v205 offset:2048
	ds_read_b128 v[154:157], v205 offset:4096
	ds_read_b128 v[158:161], v205 offset:6144
	v_add_u32_e32 v204, 0x18000, v201
	v_add_u32_e32 v205, 0x18000, v203
	ds_read_b128 v[212:215], v204 offset:0
	ds_read_b128 v[216:219], v204 offset:2048
	ds_read_b128 v[220:223], v204 offset:4096
	ds_read_b128 v[224:227], v204 offset:6144
	ds_read_b128 v[228:231], v205 offset:0
	ds_read_b128 v[232:235], v205 offset:2048
	ds_read_b128 v[236:239], v205 offset:4096
	ds_read_b128 v[240:243], v205 offset:6144
	s_add_u32 m0, s76, 0xc000
	s_nop 0
	global_load_lds_dwordx4 v196, s[68:69]
	s_add_u32 m0, s76, 0xe000
	s_nop 0
	global_load_lds_dwordx4 v197, s[68:69]
	s_add_u32 m0, s76, 0x10000
	s_nop 0
	global_load_lds_dwordx4 v198, s[68:69]
	s_add_u32 m0, s76, 0x12000
	s_nop 0
	global_load_lds_dwordx4 v199, s[68:69]
	s_add_u32 m0, s76, 0x14000
	s_nop 0
	global_load_lds_dwordx4 v196, s[70:71]
	s_add_u32 m0, s76, 0x16000
	s_nop 0
	global_load_lds_dwordx4 v197, s[70:71]
	s_add_u32 s68, s68, 0x80
	s_addc_u32 s69, s69, 0
	s_add_u32 s70, s70, 0x80
	s_addc_u32 s71, s71, 0
	s_waitcnt lgkmcnt(0)
	s_barrier
	v_mfma_f32_16x16x32_bf16 v[2:5], v[146:149], v[130:133], v[2:5]
	v_mfma_f32_16x16x32_bf16 v[6:9], v[150:153], v[130:133], v[6:9]
	v_mfma_f32_16x16x32_bf16 v[10:13], v[154:157], v[130:133], v[10:13]
	v_mfma_f32_16x16x32_bf16 v[14:17], v[158:161], v[130:133], v[14:17]
	v_mfma_f32_16x16x32_bf16 v[18:21], v[146:149], v[134:137], v[18:21]
	v_mfma_f32_16x16x32_bf16 v[22:25], v[150:153], v[134:137], v[22:25]
	v_mfma_f32_16x16x32_bf16 v[26:29], v[154:157], v[134:137], v[26:29]
	v_mfma_f32_16x16x32_bf16 v[30:33], v[158:161], v[134:137], v[30:33]
	v_mfma_f32_16x16x32_bf16 v[34:37], v[146:149], v[138:141], v[34:37]
	v_mfma_f32_16x16x32_bf16 v[38:41], v[150:153], v[138:141], v[38:41]
	v_mfma_f32_16x16x32_bf16 v[42:45], v[154:157], v[138:141], v[42:45]
	v_mfma_f32_16x16x32_bf16 v[46:49], v[158:161], v[138:141], v[46:49]
	v_mfma_f32_16x16x32_bf16 v[50:53], v[146:149], v[142:145], v[50:53]
	v_mfma_f32_16x16x32_bf16 v[54:57], v[150:153], v[142:145], v[54:57]
	v_mfma_f32_16x16x32_bf16 v[58:61], v[154:157], v[142:145], v[58:61]
	v_mfma_f32_16x16x32_bf16 v[62:65], v[158:161], v[142:145], v[62:65]
	v_mfma_f32_16x16x32_bf16 v[2:5], v[228:231], v[212:215], v[2:5]
	v_mfma_f32_16x16x32_bf16 v[6:9], v[232:235], v[212:215], v[6:9]
	v_mfma_f32_16x16x32_bf16 v[10:13], v[236:239], v[212:215], v[10:13]
	v_mfma_f32_16x16x32_bf16 v[14:17], v[240:243], v[212:215], v[14:17]
	v_mfma_f32_16x16x32_bf16 v[18:21], v[228:231], v[216:219], v[18:21]
	v_mfma_f32_16x16x32_bf16 v[22:25], v[232:235], v[216:219], v[22:25]
	v_mfma_f32_16x16x32_bf16 v[26:29], v[236:239], v[216:219], v[26:29]
	v_mfma_f32_16x16x32_bf16 v[30:33], v[240:243], v[216:219], v[30:33]
	v_mfma_f32_16x16x32_bf16 v[34:37], v[228:231], v[220:223], v[34:37]
	v_mfma_f32_16x16x32_bf16 v[38:41], v[232:235], v[220:223], v[38:41]
	v_mfma_f32_16x16x32_bf16 v[42:45], v[236:239], v[220:223], v[42:45]
	v_mfma_f32_16x16x32_bf16 v[46:49], v[240:243], v[220:223], v[46:49]
	v_mfma_f32_16x16x32_bf16 v[50:53], v[228:231], v[224:227], v[50:53]
	v_mfma_f32_16x16x32_bf16 v[54:57], v[232:235], v[224:227], v[54:57]
	v_mfma_f32_16x16x32_bf16 v[58:61], v[236:239], v[224:227], v[58:61]
	v_mfma_f32_16x16x32_bf16 v[62:65], v[240:243], v[224:227], v[62:65]
	s_waitcnt vmcnt(6)
	s_barrier
	v_add_u32_e32 v204, 0x0, v200
	v_add_u32_e32 v205, 0x0, v202
	ds_read_b128 v[130:133], v204 offset:0
	ds_read_b128 v[134:137], v204 offset:2048
	ds_read_b128 v[138:141], v204 offset:4096
	ds_read_b128 v[142:145], v204 offset:6144
	ds_read_b128 v[146:149], v205 offset:0
	ds_read_b128 v[150:153], v205 offset:2048
	ds_read_b128 v[154:157], v205 offset:4096
	ds_read_b128 v[158:161], v205 offset:6144
	v_add_u32_e32 v204, 0x0, v201
	v_add_u32_e32 v205, 0x0, v203
	ds_read_b128 v[212:215], v204 offset:0
	ds_read_b128 v[216:219], v204 offset:2048
	ds_read_b128 v[220:223], v204 offset:4096
	ds_read_b128 v[224:227], v204 offset:6144
	ds_read_b128 v[228:231], v205 offset:0
	ds_read_b128 v[232:235], v205 offset:2048
	ds_read_b128 v[236:239], v205 offset:4096
	ds_read_b128 v[240:243], v205 offset:6144
	s_add_u32 m0, s76, 0x18000
	s_nop 0
	global_load_lds_dwordx4 v196, s[68:69]
	s_add_u32 m0, s76, 0x1a000
	s_nop 0
	global_load_lds_dwordx4 v197, s[68:69]
	s_add_u32 m0, s76, 0x1c000
	s_nop 0
	global_load_lds_dwordx4 v198, s[68:69]
	s_add_u32 m0, s76, 0x1e000
	s_nop 0
	global_load_lds_dwordx4 v199, s[68:69]
	s_add_u32 m0, s76, 0x20000
	s_nop 0
	global_load_lds_dwordx4 v196, s[70:71]
	s_add_u32 m0, s76, 0x22000
	s_nop 0
	global_load_lds_dwordx4 v197, s[70:71]
	s_add_u32 s68, s68, 0x80
	s_addc_u32 s69, s69, 0
	s_add_u32 s70, s70, 0x80
	s_addc_u32 s71, s71, 0
	s_waitcnt lgkmcnt(0)
	s_barrier
	v_mfma_f32_16x16x32_bf16 v[2:5], v[146:149], v[130:133], v[2:5]
	v_mfma_f32_16x16x32_bf16 v[6:9], v[150:153], v[130:133], v[6:9]
	v_mfma_f32_16x16x32_bf16 v[10:13], v[154:157], v[130:133], v[10:13]
	v_mfma_f32_16x16x32_bf16 v[14:17], v[158:161], v[130:133], v[14:17]
	v_mfma_f32_16x16x32_bf16 v[18:21], v[146:149], v[134:137], v[18:21]
	v_mfma_f32_16x16x32_bf16 v[22:25], v[150:153], v[134:137], v[22:25]
	v_mfma_f32_16x16x32_bf16 v[26:29], v[154:157], v[134:137], v[26:29]
	v_mfma_f32_16x16x32_bf16 v[30:33], v[158:161], v[134:137], v[30:33]
	v_mfma_f32_16x16x32_bf16 v[34:37], v[146:149], v[138:141], v[34:37]
	v_mfma_f32_16x16x32_bf16 v[38:41], v[150:153], v[138:141], v[38:41]
	v_mfma_f32_16x16x32_bf16 v[42:45], v[154:157], v[138:141], v[42:45]
	v_mfma_f32_16x16x32_bf16 v[46:49], v[158:161], v[138:141], v[46:49]
	v_mfma_f32_16x16x32_bf16 v[50:53], v[146:149], v[142:145], v[50:53]
	v_mfma_f32_16x16x32_bf16 v[54:57], v[150:153], v[142:145], v[54:57]
	v_mfma_f32_16x16x32_bf16 v[58:61], v[154:157], v[142:145], v[58:61]
	v_mfma_f32_16x16x32_bf16 v[62:65], v[158:161], v[142:145], v[62:65]
	v_mfma_f32_16x16x32_bf16 v[2:5], v[228:231], v[212:215], v[2:5]
	v_mfma_f32_16x16x32_bf16 v[6:9], v[232:235], v[212:215], v[6:9]
	v_mfma_f32_16x16x32_bf16 v[10:13], v[236:239], v[212:215], v[10:13]
	v_mfma_f32_16x16x32_bf16 v[14:17], v[240:243], v[212:215], v[14:17]
	v_mfma_f32_16x16x32_bf16 v[18:21], v[228:231], v[216:219], v[18:21]
	v_mfma_f32_16x16x32_bf16 v[22:25], v[232:235], v[216:219], v[22:25]
	v_mfma_f32_16x16x32_bf16 v[26:29], v[236:239], v[216:219], v[26:29]
	v_mfma_f32_16x16x32_bf16 v[30:33], v[240:243], v[216:219], v[30:33]
	v_mfma_f32_16x16x32_bf16 v[34:37], v[228:231], v[220:223], v[34:37]
	v_mfma_f32_16x16x32_bf16 v[38:41], v[232:235], v[220:223], v[38:41]
	v_mfma_f32_16x16x32_bf16 v[42:45], v[236:239], v[220:223], v[42:45]
	v_mfma_f32_16x16x32_bf16 v[46:49], v[240:243], v[220:223], v[46:49]
	v_mfma_f32_16x16x32_bf16 v[50:53], v[228:231], v[224:227], v[50:53]
	v_mfma_f32_16x16x32_bf16 v[54:57], v[232:235], v[224:227], v[54:57]
	v_mfma_f32_16x16x32_bf16 v[58:61], v[236:239], v[224:227], v[58:61]
	v_mfma_f32_16x16x32_bf16 v[62:65], v[240:243], v[224:227], v[62:65]
	s_waitcnt vmcnt(6)
	s_barrier
	v_add_u32_e32 v204, 0xc000, v200
	v_add_u32_e32 v205, 0xc000, v202
	ds_read_b128 v[130:133], v204 offset:0
	ds_read_b128 v[134:137], v204 offset:2048
	ds_read_b128 v[138:141], v204 offset:4096
	ds_read_b128 v[142:145], v204 offset:6144
	ds_read_b128 v[146:149], v205 offset:0
	ds_read_b128 v[150:153], v205 offset:2048
	ds_read_b128 v[154:157], v205 offset:4096
	ds_read_b128 v[158:161], v205 offset:6144
	v_add_u32_e32 v204, 0xc000, v201
	v_add_u32_e32 v205, 0xc000, v203
	ds_read_b128 v[212:215], v204 offset:0
	ds_read_b128 v[216:219], v204 offset:2048
	ds_read_b128 v[220:223], v204 offset:4096
	ds_read_b128 v[224:227], v204 offset:6144
	ds_read_b128 v[228:231], v205 offset:0
	ds_read_b128 v[232:235], v205 offset:2048
	ds_read_b128 v[236:239], v205 offset:4096
	ds_read_b128 v[240:243], v205 offset:6144
	s_add_u32 m0, s76, 0x0
	s_nop 0
	global_load_lds_dwordx4 v196, s[68:69]
	s_add_u32 m0, s76, 0x2000
	s_nop 0
	global_load_lds_dwordx4 v197, s[68:69]
	s_add_u32 m0, s76, 0x4000
	s_nop 0
	global_load_lds_dwordx4 v198, s[68:69]
	s_add_u32 m0, s76, 0x6000
	s_nop 0
	global_load_lds_dwordx4 v199, s[68:69]
	s_add_u32 m0, s76, 0x8000
	s_nop 0
	global_load_lds_dwordx4 v196, s[70:71]
	s_add_u32 m0, s76, 0xa000
	s_nop 0
	global_load_lds_dwordx4 v197, s[70:71]
	s_add_u32 s68, s68, 0x80
	s_addc_u32 s69, s69, 0
	s_add_u32 s70, s70, 0x80
	s_addc_u32 s71, s71, 0
	s_waitcnt lgkmcnt(0)
	s_barrier
	v_mfma_f32_16x16x32_bf16 v[2:5], v[146:149], v[130:133], v[2:5]
	v_mfma_f32_16x16x32_bf16 v[6:9], v[150:153], v[130:133], v[6:9]
	v_mfma_f32_16x16x32_bf16 v[10:13], v[154:157], v[130:133], v[10:13]
	v_mfma_f32_16x16x32_bf16 v[14:17], v[158:161], v[130:133], v[14:17]
	v_mfma_f32_16x16x32_bf16 v[18:21], v[146:149], v[134:137], v[18:21]
	v_mfma_f32_16x16x32_bf16 v[22:25], v[150:153], v[134:137], v[22:25]
	v_mfma_f32_16x16x32_bf16 v[26:29], v[154:157], v[134:137], v[26:29]
	v_mfma_f32_16x16x32_bf16 v[30:33], v[158:161], v[134:137], v[30:33]
	v_mfma_f32_16x16x32_bf16 v[34:37], v[146:149], v[138:141], v[34:37]
	v_mfma_f32_16x16x32_bf16 v[38:41], v[150:153], v[138:141], v[38:41]
	v_mfma_f32_16x16x32_bf16 v[42:45], v[154:157], v[138:141], v[42:45]
	v_mfma_f32_16x16x32_bf16 v[46:49], v[158:161], v[138:141], v[46:49]
	v_mfma_f32_16x16x32_bf16 v[50:53], v[146:149], v[142:145], v[50:53]
	v_mfma_f32_16x16x32_bf16 v[54:57], v[150:153], v[142:145], v[54:57]
	v_mfma_f32_16x16x32_bf16 v[58:61], v[154:157], v[142:145], v[58:61]
	v_mfma_f32_16x16x32_bf16 v[62:65], v[158:161], v[142:145], v[62:65]
	v_mfma_f32_16x16x32_bf16 v[2:5], v[228:231], v[212:215], v[2:5]
	v_mfma_f32_16x16x32_bf16 v[6:9], v[232:235], v[212:215], v[6:9]
	v_mfma_f32_16x16x32_bf16 v[10:13], v[236:239], v[212:215], v[10:13]
	v_mfma_f32_16x16x32_bf16 v[14:17], v[240:243], v[212:215], v[14:17]
	v_mfma_f32_16x16x32_bf16 v[18:21], v[228:231], v[216:219], v[18:21]
	v_mfma_f32_16x16x32_bf16 v[22:25], v[232:235], v[216:219], v[22:25]
	v_mfma_f32_16x16x32_bf16 v[26:29], v[236:239], v[216:219], v[26:29]
	v_mfma_f32_16x16x32_bf16 v[30:33], v[240:243], v[216:219], v[30:33]
	v_mfma_f32_16x16x32_bf16 v[34:37], v[228:231], v[220:223], v[34:37]
	v_mfma_f32_16x16x32_bf16 v[38:41], v[232:235], v[220:223], v[38:41]
	v_mfma_f32_16x16x32_bf16 v[42:45], v[236:239], v[220:223], v[42:45]
	v_mfma_f32_16x16x32_bf16 v[46:49], v[240:243], v[220:223], v[46:49]
	v_mfma_f32_16x16x32_bf16 v[50:53], v[228:231], v[224:227], v[50:53]
	v_mfma_f32_16x16x32_bf16 v[54:57], v[232:235], v[224:227], v[54:57]
	v_mfma_f32_16x16x32_bf16 v[58:61], v[236:239], v[224:227], v[58:61]
	v_mfma_f32_16x16x32_bf16 v[62:65], v[240:243], v[224:227], v[62:65]
	s_waitcnt vmcnt(6)
	s_barrier
	s_add_i32 s16, s16, -1
	s_cmp_lg_u32 s16, 0
	s_cbranch_scc1 .Lop_kloop1
	v_add_u32_e32 v204, 0x18000, v200
	v_add_u32_e32 v205, 0x18000, v202
	ds_read_b128 v[130:133], v204 offset:0
	ds_read_b128 v[134:137], v204 offset:2048
	ds_read_b128 v[138:141], v204 offset:4096
	ds_read_b128 v[142:145], v204 offset:6144
	ds_read_b128 v[146:149], v205 offset:0
	ds_read_b128 v[150:153], v205 offset:2048
	ds_read_b128 v[154:157], v205 offset:4096
	ds_read_b128 v[158:161], v205 offset:6144
	v_add_u32_e32 v204, 0x18000, v201
	v_add_u32_e32 v205, 0x18000, v203
	ds_read_b128 v[212:215], v204 offset:0
	ds_read_b128 v[216:219], v204 offset:2048
	ds_read_b128 v[220:223], v204 offset:4096
	ds_read_b128 v[224:227], v204 offset:6144
	ds_read_b128 v[228:231], v205 offset:0
	ds_read_b128 v[232:235], v205 offset:2048
	ds_read_b128 v[236:239], v205 offset:4096
	ds_read_b128 v[240:243], v205 offset:6144
	s_waitcnt lgkmcnt(0)
	s_barrier
	v_mfma_f32_16x16x32_bf16 v[2:5], v[146:149], v[130:133], v[2:5]
	v_mfma_f32_16x16x32_bf16 v[6:9], v[150:153], v[130:133], v[6:9]
	v_mfma_f32_16x16x32_bf16 v[10:13], v[154:157], v[130:133], v[10:13]
	v_mfma_f32_16x16x32_bf16 v[14:17], v[158:161], v[130:133], v[14:17]
	v_mfma_f32_16x16x32_bf16 v[18:21], v[146:149], v[134:137], v[18:21]
	v_mfma_f32_16x16x32_bf16 v[22:25], v[150:153], v[134:137], v[22:25]
	v_mfma_f32_16x16x32_bf16 v[26:29], v[154:157], v[134:137], v[26:29]
	v_mfma_f32_16x16x32_bf16 v[30:33], v[158:161], v[134:137], v[30:33]
	v_mfma_f32_16x16x32_bf16 v[34:37], v[146:149], v[138:141], v[34:37]
	v_mfma_f32_16x16x32_bf16 v[38:41], v[150:153], v[138:141], v[38:41]
	v_mfma_f32_16x16x32_bf16 v[42:45], v[154:157], v[138:141], v[42:45]
	v_mfma_f32_16x16x32_bf16 v[46:49], v[158:161], v[138:141], v[46:49]
	v_mfma_f32_16x16x32_bf16 v[50:53], v[146:149], v[142:145], v[50:53]
	v_mfma_f32_16x16x32_bf16 v[54:57], v[150:153], v[142:145], v[54:57]
	v_mfma_f32_16x16x32_bf16 v[58:61], v[154:157], v[142:145], v[58:61]
	v_mfma_f32_16x16x32_bf16 v[62:65], v[158:161], v[142:145], v[62:65]
	v_mfma_f32_16x16x32_bf16 v[2:5], v[228:231], v[212:215], v[2:5]
	v_mfma_f32_16x16x32_bf16 v[6:9], v[232:235], v[212:215], v[6:9]
	v_mfma_f32_16x16x32_bf16 v[10:13], v[236:239], v[212:215], v[10:13]
	v_mfma_f32_16x16x32_bf16 v[14:17], v[240:243], v[212:215], v[14:17]
	v_mfma_f32_16x16x32_bf16 v[18:21], v[228:231], v[216:219], v[18:21]
	v_mfma_f32_16x16x32_bf16 v[22:25], v[232:235], v[216:219], v[22:25]
	v_mfma_f32_16x16x32_bf16 v[26:29], v[236:239], v[216:219], v[26:29]
	v_mfma_f32_16x16x32_bf16 v[30:33], v[240:243], v[216:219], v[30:33]
	v_mfma_f32_16x16x32_bf16 v[34:37], v[228:231], v[220:223], v[34:37]
	v_mfma_f32_16x16x32_bf16 v[38:41], v[232:235], v[220:223], v[38:41]
	v_mfma_f32_16x16x32_bf16 v[42:45], v[236:239], v[220:223], v[42:45]
	v_mfma_f32_16x16x32_bf16 v[46:49], v[240:243], v[220:223], v[46:49]
	v_mfma_f32_16x16x32_bf16 v[50:53], v[228:231], v[224:227], v[50:53]
	v_mfma_f32_16x16x32_bf16 v[54:57], v[232:235], v[224:227], v[54:57]
	v_mfma_f32_16x16x32_bf16 v[58:61], v[236:239], v[224:227], v[58:61]
	v_mfma_f32_16x16x32_bf16 v[62:65], v[240:243], v[224:227], v[62:65]
	s_waitcnt vmcnt(0)
	s_barrier
	v_add_u32_e32 v204, 0x0, v200
	v_add_u32_e32 v205, 0x0, v202
	ds_read_b128 v[130:133], v204 offset:0
	ds_read_b128 v[134:137], v204 offset:2048
	ds_read_b128 v[138:141], v204 offset:4096
	ds_read_b128 v[142:145], v204 offset:6144
	ds_read_b128 v[146:149], v205 offset:0
	ds_read_b128 v[150:153], v205 offset:2048
	ds_read_b128 v[154:157], v205 offset:4096
	ds_read_b128 v[158:161], v205 offset:6144
	v_add_u32_e32 v204, 0x0, v201
	v_add_u32_e32 v205, 0x0, v203
	ds_read_b128 v[212:215], v204 offset:0
	ds_read_b128 v[216:219], v204 offset:2048
	ds_read_b128 v[220:223], v204 offset:4096
	ds_read_b128 v[224:227], v204 offset:6144
	ds_read_b128 v[228:231], v205 offset:0
	ds_read_b128 v[232:235], v205 offset:2048
	ds_read_b128 v[236:239], v205 offset:4096
	ds_read_b128 v[240:243], v205 offset:6144
	s_waitcnt lgkmcnt(0)
	s_barrier
	v_mfma_f32_16x16x32_bf16 v[2:5], v[146:149], v[130:133], v[2:5]
	v_mfma_f32_16x16x32_bf16 v[6:9], v[150:153], v[130:133], v[6:9]
	v_mfma_f32_16x16x32_bf16 v[10:13], v[154:157], v[130:133], v[10:13]
	v_mfma_f32_16x16x32_bf16 v[14:17], v[158:161], v[130:133], v[14:17]
	v_mfma_f32_16x16x32_bf16 v[18:21], v[146:149], v[134:137], v[18:21]
	v_mfma_f32_16x16x32_bf16 v[22:25], v[150:153], v[134:137], v[22:25]
	v_mfma_f32_16x16x32_bf16 v[26:29], v[154:157], v[134:137], v[26:29]
	v_mfma_f32_16x16x32_bf16 v[30:33], v[158:161], v[134:137], v[30:33]
	v_mfma_f32_16x16x32_bf16 v[34:37], v[146:149], v[138:141], v[34:37]
	v_mfma_f32_16x16x32_bf16 v[38:41], v[150:153], v[138:141], v[38:41]
	v_mfma_f32_16x16x32_bf16 v[42:45], v[154:157], v[138:141], v[42:45]
	v_mfma_f32_16x16x32_bf16 v[46:49], v[158:161], v[138:141], v[46:49]
	v_mfma_f32_16x16x32_bf16 v[50:53], v[146:149], v[142:145], v[50:53]
	v_mfma_f32_16x16x32_bf16 v[54:57], v[150:153], v[142:145], v[54:57]
	v_mfma_f32_16x16x32_bf16 v[58:61], v[154:157], v[142:145], v[58:61]
	v_mfma_f32_16x16x32_bf16 v[62:65], v[158:161], v[142:145], v[62:65]
	v_mfma_f32_16x16x32_bf16 v[2:5], v[228:231], v[212:215], v[2:5]
	v_mfma_f32_16x16x32_bf16 v[6:9], v[232:235], v[212:215], v[6:9]
	v_mfma_f32_16x16x32_bf16 v[10:13], v[236:239], v[212:215], v[10:13]
	v_mfma_f32_16x16x32_bf16 v[14:17], v[240:243], v[212:215], v[14:17]
	v_mfma_f32_16x16x32_bf16 v[18:21], v[228:231], v[216:219], v[18:21]
	v_mfma_f32_16x16x32_bf16 v[22:25], v[232:235], v[216:219], v[22:25]
	v_mfma_f32_16x16x32_bf16 v[26:29], v[236:239], v[216:219], v[26:29]
	v_mfma_f32_16x16x32_bf16 v[30:33], v[240:243], v[216:219], v[30:33]
	v_mfma_f32_16x16x32_bf16 v[34:37], v[228:231], v[220:223], v[34:37]
	v_mfma_f32_16x16x32_bf16 v[38:41], v[232:235], v[220:223], v[38:41]
	v_mfma_f32_16x16x32_bf16 v[42:45], v[236:239], v[220:223], v[42:45]
	v_mfma_f32_16x16x32_bf16 v[46:49], v[240:243], v[220:223], v[46:49]
	v_mfma_f32_16x16x32_bf16 v[50:53], v[228:231], v[224:227], v[50:53]
	v_mfma_f32_16x16x32_bf16 v[54:57], v[232:235], v[224:227], v[54:57]
	v_mfma_f32_16x16x32_bf16 v[58:61], v[236:239], v[224:227], v[58:61]
	v_mfma_f32_16x16x32_bf16 v[62:65], v[240:243], v[224:227], v[62:65]
	s_barrier
	s_branch .Lop_join
.Lop_streamB:
	s_barrier
	v_add_u32_e32 v204, 0x0, v200
	v_add_u32_e32 v205, 0x0, v202
	ds_read_b128 v[130:133], v204 offset:0
	ds_read_b128 v[134:137], v204 offset:2048
	ds_read_b128 v[138:141], v204 offset:4096
	ds_read_b128 v[142:145], v204 offset:6144
	ds_read_b128 v[146:149], v205 offset:0
	ds_read_b128 v[150:153], v205 offset:2048
	ds_read_b128 v[154:157], v205 offset:4096
	ds_read_b128 v[158:161], v205 offset:6144
	v_add_u32_e32 v204, 0x0, v201
	v_add_u32_e32 v205, 0x0, v203
	ds_read_b128 v[212:215], v204 offset:0
	ds_read_b128 v[216:219], v204 offset:2048
	ds_read_b128 v[220:223], v204 offset:4096
	ds_read_b128 v[224:227], v204 offset:6144
	ds_read_b128 v[228:231], v205 offset:0
	ds_read_b128 v[232:235], v205 offset:2048
	ds_read_b128 v[236:239], v205 offset:4096
	ds_read_b128 v[240:243], v205 offset:6144
	s_add_u32 m0, s76, 0x18000
	s_nop 0
	global_load_lds_dwordx4 v196, s[68:69]
	s_add_u32 m0, s76, 0x1a000
	s_nop 0
	global_load_lds_dwordx4 v197, s[68:69]
	s_add_u32 m0, s76, 0x1c000
	s_nop 0
	global_load_lds_dwordx4 v198, s[68:69]
	s_add_u32 m0, s76, 0x1e000
	s_nop 0
	global_load_lds_dwordx4 v199, s[68:69]
	s_add_u32 m0, s76, 0x20000
	s_nop 0
	global_load_lds_dwordx4 v196, s[70:71]
	s_add_u32 m0, s76, 0x22000
	s_nop 0
	global_load_lds_dwordx4 v197, s[70:71]
	s_add_u32 s68, s68, 0x80
	s_addc_u32 s69, s69, 0
	s_add_u32 s70, s70, 0x80
	s_addc_u32 s71, s71, 0
	global_load_dwordx4 v[174:177], v190, s[72:73] offset:0
	global_load_dwordx4 v[178:181], v190, s[72:73] offset:64
	global_load_dwordx4 v[182:185], v190, s[72:73] offset:128
	global_load_dwordx4 v[186:189], v190, s[72:73] offset:192
	global_load_dwordx4 v[66:69], v191, s[14:15]
	v_add_u32_e32 v170, s38, v191
	global_load_dwordx4 v[70:73], v170, s[14:15]
	v_add_u32_e32 v170, s39, v191
	global_load_dwordx4 v[74:77], v170, s[14:15]
	s_waitcnt vmcnt(13)
	s_waitcnt lgkmcnt(0)
	s_barrier
	v_mfma_f32_16x16x32_bf16 v[2:5], v[146:149], v[130:133], 0
	v_mfma_f32_16x16x32_bf16 v[6:9], v[150:153], v[130:133], 0
	v_mfma_f32_16x16x32_bf16 v[10:13], v[154:157], v[130:133], 0
	v_mfma_f32_16x16x32_bf16 v[14:17], v[158:161], v[130:133], 0
	v_mfma_f32_16x16x32_bf16 v[18:21], v[146:149], v[134:137], 0
	v_mfma_f32_16x16x32_bf16 v[22:25], v[150:153], v[134:137], 0
	v_mfma_f32_16x16x32_bf16 v[26:29], v[154:157], v[134:137], 0
	v_mfma_f32_16x16x32_bf16 v[30:33], v[158:161], v[134:137], 0
	v_mfma_f32_16x16x32_bf16 v[34:37], v[146:149], v[138:141], 0
	v_mfma_f32_16x16x32_bf16 v[38:41], v[150:153], v[138:141], 0
	v_mfma_f32_16x16x32_bf16 v[42:45], v[154:157], v[138:141], 0
	v_mfma_f32_16x16x32_bf16 v[46:49], v[158:161], v[138:141], 0
	v_mfma_f32_16x16x32_bf16 v[50:53], v[146:149], v[142:145], 0
	v_mfma_f32_16x16x32_bf16 v[54:57], v[150:153], v[142:145], 0
	v_mfma_f32_16x16x32_bf16 v[58:61], v[154:157], v[142:145], 0
	v_mfma_f32_16x16x32_bf16 v[62:65], v[158:161], v[142:145], 0
	v_mfma_f32_16x16x32_bf16 v[2:5], v[228:231], v[212:215], v[2:5]
	v_mfma_f32_16x16x32_bf16 v[6:9], v[232:235], v[212:215], v[6:9]
	v_mfma_f32_16x16x32_bf16 v[10:13], v[236:239], v[212:215], v[10:13]
	v_mfma_f32_16x16x32_bf16 v[14:17], v[240:243], v[212:215], v[14:17]
	v_mfma_f32_16x16x32_bf16 v[18:21], v[228:231], v[216:219], v[18:21]
	v_mfma_f32_16x16x32_bf16 v[22:25], v[232:235], v[216:219], v[22:25]
	v_mfma_f32_16x16x32_bf16 v[26:29], v[236:239], v[216:219], v[26:29]
	v_mfma_f32_16x16x32_bf16 v[30:33], v[240:243], v[216:219], v[30:33]
	v_mfma_f32_16x16x32_bf16 v[34:37], v[228:231], v[220:223], v[34:37]
	v_mfma_f32_16x16x32_bf16 v[38:41], v[232:235], v[220:223], v[38:41]
	v_mfma_f32_16x16x32_bf16 v[42:45], v[236:239], v[220:223], v[42:45]
	v_mfma_f32_16x16x32_bf16 v[46:49], v[240:243], v[220:223], v[46:49]
	v_mfma_f32_16x16x32_bf16 v[50:53], v[228:231], v[224:227], v[50:53]
	v_mfma_f32_16x16x32_bf16 v[54:57], v[232:235], v[224:227], v[54:57]
	v_mfma_f32_16x16x32_bf16 v[58:61], v[236:239], v[224:227], v[58:61]
	v_mfma_f32_16x16x32_bf16 v[62:65], v[240:243], v[224:227], v[62:65]
	s_barrier
	v_add_u32_e32 v204, 0xc000, v200
	v_add_u32_e32 v205, 0xc000, v202
	ds_read_b128 v[130:133], v204 offset:0
	ds_read_b128 v[134:137], v204 offset:2048
	ds_read_b128 v[138:141], v204 offset:4096
	ds_read_b128 v[142:145], v204 offset:6144
	ds_read_b128 v[146:149], v205 offset:0
	ds_read_b128 v[150:153], v205 offset:2048
	ds_read_b128 v[154:157], v205 offset:4096
	ds_read_b128 v[158:161], v205 offset:6144
	v_add_u32_e32 v204, 0xc000, v201
	v_add_u32_e32 v205, 0xc000, v203
	ds_read_b128 v[212:215], v204 offset:0
	ds_read_b128 v[216:219], v204 offset:2048
	ds_read_b128 v[220:223], v204 offset:4096
	ds_read_b128 v[224:227], v204 offset:6144
	ds_read_b128 v[228:231], v205 offset:0
	ds_read_b128 v[232:235], v205 offset:2048
	ds_read_b128 v[236:239], v205 offset:4096
	ds_read_b128 v[240:243], v205 offset:6144
	s_add_u32 m0, s76, 0x0
	s_nop 0
	global_load_lds_dwordx4 v196, s[68:69]
	s_add_u32 m0, s76, 0x2000
	s_nop 0
	global_load_lds_dwordx4 v197, s[68:69]
	s_add_u32 m0, s76, 0x4000
	s_nop 0
	global_load_lds_dwordx4 v198, s[68:69]
	s_add_u32 m0, s76, 0x6000
	s_nop 0
	global_load_lds_dwordx4 v199, s[68:69]
	s_add_u32 m0, s76, 0x8000
	s_nop 0
	global_load_lds_dwordx4 v196, s[70:71]
	s_add_u32 m0, s76, 0xa000
	s_nop 0
	global_load_lds_dwordx4 v197, s[70:71]
	s_add_u32 s68, s68, 0x80
	s_addc_u32 s69, s69, 0
	s_add_u32 s70, s70, 0x80
	s_addc_u32 s71, s71, 0
	v_add_u32_e32 v170, s40, v191
	global_load_dwordx4 v[78:81], v170, s[14:15]
	global_load_dwordx4 v[82:85], v192, s[14:15]
	v_add_u32_e32 v170, s38, v192
	global_load_dwordx4 v[86:89], v170, s[14:15]
	v_add_u32_e32 v170, s39, v192
	global_load_dwordx4 v[90:93], v170, s[14:15]
	v_add_u32_e32 v170, s40, v192
	global_load_dwordx4 v[94:97], v170, s[14:15]
	global_load_dwordx4 v[98:101], v193, s[14:15]
	v_add_u32_e32 v170, s38, v193
	global_load_dwordx4 v[102:105], v170, s[14:15]
	s_waitcnt vmcnt(20)
	s_waitcnt lgkmcnt(0)
	s_barrier
	v_mfma_f32_16x16x32_bf16 v[2:5], v[146:149], v[130:133], v[2:5]
	v_mfma_f32_16x16x32_bf16 v[6:9], v[150:153], v[130:133], v[6:9]
	v_mfma_f32_16x16x32_bf16 v[10:13], v[154:157], v[130:133], v[10:13]
	v_mfma_f32_16x16x32_bf16 v[14:17], v[158:161], v[130:133], v[14:17]
	v_mfma_f32_16x16x32_bf16 v[18:21], v[146:149], v[134:137], v[18:21]
	v_mfma_f32_16x16x32_bf16 v[22:25], v[150:153], v[134:137], v[22:25]
	v_mfma_f32_16x16x32_bf16 v[26:29], v[154:157], v[134:137], v[26:29]
	v_mfma_f32_16x16x32_bf16 v[30:33], v[158:161], v[134:137], v[30:33]
	v_mfma_f32_16x16x32_bf16 v[34:37], v[146:149], v[138:141], v[34:37]
	v_mfma_f32_16x16x32_bf16 v[38:41], v[150:153], v[138:141], v[38:41]
	v_mfma_f32_16x16x32_bf16 v[42:45], v[154:157], v[138:141], v[42:45]
	v_mfma_f32_16x16x32_bf16 v[46:49], v[158:161], v[138:141], v[46:49]
	v_mfma_f32_16x16x32_bf16 v[50:53], v[146:149], v[142:145], v[50:53]
	v_mfma_f32_16x16x32_bf16 v[54:57], v[150:153], v[142:145], v[54:57]
	v_mfma_f32_16x16x32_bf16 v[58:61], v[154:157], v[142:145], v[58:61]
	v_mfma_f32_16x16x32_bf16 v[62:65], v[158:161], v[142:145], v[62:65]
	v_mfma_f32_16x16x32_bf16 v[2:5], v[228:231], v[212:215], v[2:5]
	v_mfma_f32_16x16x32_bf16 v[6:9], v[232:235], v[212:215], v[6:9]
	v_mfma_f32_16x16x32_bf16 v[10:13], v[236:239], v[212:215], v[10:13]
	v_mfma_f32_16x16x32_bf16 v[14:17], v[240:243], v[212:215], v[14:17]
	v_mfma_f32_16x16x32_bf16 v[18:21], v[228:231], v[216:219], v[18:21]
	v_mfma_f32_16x16x32_bf16 v[22:25], v[232:235], v[216:219], v[22:25]
	v_mfma_f32_16x16x32_bf16 v[26:29], v[236:239], v[216:219], v[26:29]
	v_mfma_f32_16x16x32_bf16 v[30:33], v[240:243], v[216:219], v[30:33]
	v_mfma_f32_16x16x32_bf16 v[34:37], v[228:231], v[220:223], v[34:37]
	v_mfma_f32_16x16x32_bf16 v[38:41], v[232:235], v[220:223], v[38:41]
	v_mfma_f32_16x16x32_bf16 v[42:45], v[236:239], v[220:223], v[42:45]
	v_mfma_f32_16x16x32_bf16 v[46:49], v[240:243], v[220:223], v[46:49]
	v_mfma_f32_16x16x32_bf16 v[50:53], v[228:231], v[224:227], v[50:53]
	v_mfma_f32_16x16x32_bf16 v[54:57], v[232:235], v[224:227], v[54:57]
	v_mfma_f32_16x16x32_bf16 v[58:61], v[236:239], v[224:227], v[58:61]
	v_mfma_f32_16x16x32_bf16 v[62:65], v[240:243], v[224:227], v[62:65]
	s_barrier
	v_add_u32_e32 v204, 0x18000, v200
	v_add_u32_e32 v205, 0x18000, v202
	ds_read_b128 v[130:133], v204 offset:0
	ds_read_b128 v[134:137], v204 offset:2048
	ds_read_b128 v[138:141], v204 offset:4096
	ds_read_b128 v[142:145], v204 offset:6144
	ds_read_b128 v[146:149], v205 offset:0
	ds_read_b128 v[150:153], v205 offset:2048
	ds_read_b128 v[154:157], v205 offset:4096
	ds_read_b128 v[158:161], v205 offset:6144
	v_add_u32_e32 v204, 0x18000, v201
	v_add_u32_e32 v205, 0x18000, v203
	ds_read_b128 v[212:215], v204 offset:0
	ds_read_b128 v[216:219], v204 offset:2048
	ds_read_b128 v[220:223], v204 offset:4096
	ds_read_b128 v[224:227], v204 offset:6144
	ds_read_b128 v[228:231], v205 offset:0
	ds_read_b128 v[232:235], v205 offset:2048
	ds_read_b128 v[236:239], v205 offset:4096
	ds_read_b128 v[240:243], v205 offset:6144
	s_add_u32 m0, s76, 0xc000
	s_nop 0
	global_load_lds_dwordx4 v196, s[68:69]
	s_add_u32 m0, s76, 0xe000
	s_nop 0
	global_load_lds_dwordx4 v197, s[68:69]
	s_add_u32 m0, s76, 0x10000
	s_nop 0
	global_load_lds_dwordx4 v198, s[68:69]
	s_add_u32 m0, s76, 0x12000
	s_nop 0
	global_load_lds_dwordx4 v199, s[68:69]
	s_add_u32 m0, s76, 0x14000
	s_nop 0
	global_load_lds_dwordx4 v196, s[70:71]
	s_add_u32 m0, s76, 0x16000
	s_nop 0
	global_load_lds_dwordx4 v197, s[70:71]
	s_add_u32 s68, s68, 0x80
	s_addc_u32 s69, s69, 0
	s_add_u32 s70, s70, 0x80
	s_addc_u32 s71, s71, 0
	v_add_u32_e32 v170, s39, v193
	global_load_dwordx4 v[106:109], v170, s[14:15]
	v_add_u32_e32 v170, s40, v193
	global_load_dwordx4 v[110:113], v170, s[14:15]
	global_load_dwordx4 v[114:117], v244, s[14:15]
	v_add_u32_e32 v170, s38, v244
	global_load_dwordx4 v[118:121], v170, s[14:15]
	v_add_u32_e32 v170, s39, v244
	global_load_dwordx4 v[122:125], v170, s[14:15]
	v_add_u32_e32 v170, s40, v244
	global_load_dwordx4 v[126:129], v170, s[14:15]
	s_waitcnt vmcnt(19)
	s_waitcnt lgkmcnt(0)
	s_barrier
	v_mfma_f32_16x16x32_bf16 v[2:5], v[146:149], v[130:133], v[2:5]
	v_mfma_f32_16x16x32_bf16 v[6:9], v[150:153], v[130:133], v[6:9]
	v_mfma_f32_16x16x32_bf16 v[10:13], v[154:157], v[130:133], v[10:13]
	v_mfma_f32_16x16x32_bf16 v[14:17], v[158:161], v[130:133], v[14:17]
	v_mfma_f32_16x16x32_bf16 v[18:21], v[146:149], v[134:137], v[18:21]
	v_mfma_f32_16x16x32_bf16 v[22:25], v[150:153], v[134:137], v[22:25]
	v_mfma_f32_16x16x32_bf16 v[26:29], v[154:157], v[134:137], v[26:29]
	v_mfma_f32_16x16x32_bf16 v[30:33], v[158:161], v[134:137], v[30:33]
	v_mfma_f32_16x16x32_bf16 v[34:37], v[146:149], v[138:141], v[34:37]
	v_mfma_f32_16x16x32_bf16 v[38:41], v[150:153], v[138:141], v[38:41]
	v_mfma_f32_16x16x32_bf16 v[42:45], v[154:157], v[138:141], v[42:45]
	v_mfma_f32_16x16x32_bf16 v[46:49], v[158:161], v[138:141], v[46:49]
	v_mfma_f32_16x16x32_bf16 v[50:53], v[146:149], v[142:145], v[50:53]
	v_mfma_f32_16x16x32_bf16 v[54:57], v[150:153], v[142:145], v[54:57]
	v_mfma_f32_16x16x32_bf16 v[58:61], v[154:157], v[142:145], v[58:61]
	v_mfma_f32_16x16x32_bf16 v[62:65], v[158:161], v[142:145], v[62:65]
	v_mfma_f32_16x16x32_bf16 v[2:5], v[228:231], v[212:215], v[2:5]
	v_mfma_f32_16x16x32_bf16 v[6:9], v[232:235], v[212:215], v[6:9]
	v_mfma_f32_16x16x32_bf16 v[10:13], v[236:239], v[212:215], v[10:13]
	v_mfma_f32_16x16x32_bf16 v[14:17], v[240:243], v[212:215], v[14:17]
	v_mfma_f32_16x16x32_bf16 v[18:21], v[228:231], v[216:219], v[18:21]
	v_mfma_f32_16x16x32_bf16 v[22:25], v[232:235], v[216:219], v[22:25]
	v_mfma_f32_16x16x32_bf16 v[26:29], v[236:239], v[216:219], v[26:29]
	v_mfma_f32_16x16x32_bf16 v[30:33], v[240:243], v[216:219], v[30:33]
	v_mfma_f32_16x16x32_bf16 v[34:37], v[228:231], v[220:223], v[34:37]
	v_mfma_f32_16x16x32_bf16 v[38:41], v[232:235], v[220:223], v[38:41]
	v_mfma_f32_16x16x32_bf16 v[42:45], v[236:239], v[220:223], v[42:45]
	v_mfma_f32_16x16x32_bf16 v[46:49], v[240:243], v[220:223], v[46:49]
	v_mfma_f32_16x16x32_bf16 v[50:53], v[228:231], v[224:227], v[50:53]
	v_mfma_f32_16x16x32_bf16 v[54:57], v[232:235], v[224:227], v[54:57]
	v_mfma_f32_16x16x32_bf16 v[58:61], v[236:239], v[224:227], v[58:61]
	v_mfma_f32_16x16x32_bf16 v[62:65], v[240:243], v[224:227], v[62:65]
	s_barrier
	v_add_u32_e32 v204, 0x0, v200
	v_add_u32_e32 v205, 0x0, v202
	ds_read_b128 v[130:133], v204 offset:0
	ds_read_b128 v[134:137], v204 offset:2048
	ds_read_b128 v[138:141], v204 offset:4096
	ds_read_b128 v[142:145], v204 offset:6144
	ds_read_b128 v[146:149], v205 offset:0
	ds_read_b128 v[150:153], v205 offset:2048
	ds_read_b128 v[154:157], v205 offset:4096
	ds_read_b128 v[158:161], v205 offset:6144
	v_add_u32_e32 v204, 0x0, v201
	v_add_u32_e32 v205, 0x0, v203
	ds_read_b128 v[212:215], v204 offset:0
	ds_read_b128 v[216:219], v204 offset:2048
	ds_read_b128 v[220:223], v204 offset:4096
	ds_read_b128 v[224:227], v204 offset:6144
	ds_read_b128 v[228:231], v205 offset:0
	ds_read_b128 v[232:235], v205 offset:2048
	ds_read_b128 v[236:239], v205 offset:4096
	ds_read_b128 v[240:243], v205 offset:6144
	s_add_u32 m0, s76, 0x18000
	s_nop 0
	global_load_lds_dwordx4 v196, s[68:69]
	s_add_u32 m0, s76, 0x1a000
	s_nop 0
	global_load_lds_dwordx4 v197, s[68:69]
	s_add_u32 m0, s76, 0x1c000
	s_nop 0
	global_load_lds_dwordx4 v198, s[68:69]
	s_add_u32 m0, s76, 0x1e000
	s_nop 0
	global_load_lds_dwordx4 v199, s[68:69]
	s_add_u32 m0, s76, 0x20000
	s_nop 0
	global_load_lds_dwordx4 v196, s[70:71]
	s_add_u32 m0, s76, 0x22000
	s_nop 0
	global_load_lds_dwordx4 v197, s[70:71]
	s_add_u32 s68, s68, 0x80
	s_addc_u32 s69, s69, 0
	s_add_u32 s70, s70, 0x80
	s_addc_u32 s71, s71, 0
	s_waitcnt vmcnt(12)
	s_waitcnt lgkmcnt(0)
	s_barrier
	v_mfma_f32_16x16x32_bf16 v[2:5], v[146:149], v[130:133], v[2:5]
	v_mfma_f32_16x16x32_bf16 v[6:9], v[150:153], v[130:133], v[6:9]
	v_mfma_f32_16x16x32_bf16 v[10:13], v[154:157], v[130:133], v[10:13]
	v_mfma_f32_16x16x32_bf16 v[14:17], v[158:161], v[130:133], v[14:17]
	v_mfma_f32_16x16x32_bf16 v[18:21], v[146:149], v[134:137], v[18:21]
	v_mfma_f32_16x16x32_bf16 v[22:25], v[150:153], v[134:137], v[22:25]
	v_mfma_f32_16x16x32_bf16 v[26:29], v[154:157], v[134:137], v[26:29]
	v_mfma_f32_16x16x32_bf16 v[30:33], v[158:161], v[134:137], v[30:33]
	v_mfma_f32_16x16x32_bf16 v[34:37], v[146:149], v[138:141], v[34:37]
	v_mfma_f32_16x16x32_bf16 v[38:41], v[150:153], v[138:141], v[38:41]
	v_mfma_f32_16x16x32_bf16 v[42:45], v[154:157], v[138:141], v[42:45]
	v_mfma_f32_16x16x32_bf16 v[46:49], v[158:161], v[138:141], v[46:49]
	v_mfma_f32_16x16x32_bf16 v[50:53], v[146:149], v[142:145], v[50:53]
	v_mfma_f32_16x16x32_bf16 v[54:57], v[150:153], v[142:145], v[54:57]
	v_mfma_f32_16x16x32_bf16 v[58:61], v[154:157], v[142:145], v[58:61]
	v_mfma_f32_16x16x32_bf16 v[62:65], v[158:161], v[142:145], v[62:65]
	v_mfma_f32_16x16x32_bf16 v[2:5], v[228:231], v[212:215], v[2:5]
	v_mfma_f32_16x16x32_bf16 v[6:9], v[232:235], v[212:215], v[6:9]
	v_mfma_f32_16x16x32_bf16 v[10:13], v[236:239], v[212:215], v[10:13]
	v_mfma_f32_16x16x32_bf16 v[14:17], v[240:243], v[212:215], v[14:17]
	v_mfma_f32_16x16x32_bf16 v[18:21], v[228:231], v[216:219], v[18:21]
	v_mfma_f32_16x16x32_bf16 v[22:25], v[232:235], v[216:219], v[22:25]
	v_mfma_f32_16x16x32_bf16 v[26:29], v[236:239], v[216:219], v[26:29]
	v_mfma_f32_16x16x32_bf16 v[30:33], v[240:243], v[216:219], v[30:33]
	v_mfma_f32_16x16x32_bf16 v[34:37], v[228:231], v[220:223], v[34:37]
	v_mfma_f32_16x16x32_bf16 v[38:41], v[232:235], v[220:223], v[38:41]
	v_mfma_f32_16x16x32_bf16 v[42:45], v[236:239], v[220:223], v[42:45]
	v_mfma_f32_16x16x32_bf16 v[46:49], v[240:243], v[220:223], v[46:49]
	v_mfma_f32_16x16x32_bf16 v[50:53], v[228:231], v[224:227], v[50:53]
	v_mfma_f32_16x16x32_bf16 v[54:57], v[232:235], v[224:227], v[54:57]
	v_mfma_f32_16x16x32_bf16 v[58:61], v[236:239], v[224:227], v[58:61]
	v_mfma_f32_16x16x32_bf16 v[62:65], v[240:243], v[224:227], v[62:65]
	s_barrier
	v_add_u32_e32 v204, 0xc000, v200
	v_add_u32_e32 v205, 0xc000, v202
	ds_read_b128 v[130:133], v204 offset:0
	ds_read_b128 v[134:137], v204 offset:2048
	ds_read_b128 v[138:141], v204 offset:4096
	ds_read_b128 v[142:145], v204 offset:6144
	ds_read_b128 v[146:149], v205 offset:0
	ds_read_b128 v[150:153], v205 offset:2048
	ds_read_b128 v[154:157], v205 offset:4096
	ds_read_b128 v[158:161], v205 offset:6144
	v_add_u32_e32 v204, 0xc000, v201
	v_add_u32_e32 v205, 0xc000, v203
	ds_read_b128 v[212:215], v204 offset:0
	ds_read_b128 v[216:219], v204 offset:2048
	ds_read_b128 v[220:223], v204 offset:4096
	ds_read_b128 v[224:227], v204 offset:6144
	ds_read_b128 v[228:231], v205 offset:0
	ds_read_b128 v[232:235], v205 offset:2048
	ds_read_b128 v[236:239], v205 offset:4096
	ds_read_b128 v[240:243], v205 offset:6144
	s_add_u32 m0, s76, 0x0
	s_nop 0
	global_load_lds_dwordx4 v196, s[68:69]
	s_add_u32 m0, s76, 0x2000
	s_nop 0
	global_load_lds_dwordx4 v197, s[68:69]
	s_add_u32 m0, s76, 0x4000
	s_nop 0
	global_load_lds_dwordx4 v198, s[68:69]
	s_add_u32 m0, s76, 0x6000
	s_nop 0
	global_load_lds_dwordx4 v199, s[68:69]
	s_add_u32 m0, s76, 0x8000
	s_nop 0
	global_load_lds_dwordx4 v196, s[70:71]
	s_add_u32 m0, s76, 0xa000
	s_nop 0
	global_load_lds_dwordx4 v197, s[70:71]
	s_add_u32 s68, s68, 0x80
	s_addc_u32 s69, s69, 0
	s_add_u32 s70, s70, 0x80
	s_addc_u32 s71, s71, 0
	s_waitcnt vmcnt(6)
	s_waitcnt lgkmcnt(0)
	s_barrier
	v_mfma_f32_16x16x32_bf16 v[2:5], v[146:149], v[130:133], v[2:5]
	v_mfma_f32_16x16x32_bf16 v[6:9], v[150:153], v[130:133], v[6:9]
	v_mfma_f32_16x16x32_bf16 v[10:13], v[154:157], v[130:133], v[10:13]
	v_mfma_f32_16x16x32_bf16 v[14:17], v[158:161], v[130:133], v[14:17]
	v_mfma_f32_16x16x32_bf16 v[18:21], v[146:149], v[134:137], v[18:21]
	v_mfma_f32_16x16x32_bf16 v[22:25], v[150:153], v[134:137], v[22:25]
	v_mfma_f32_16x16x32_bf16 v[26:29], v[154:157], v[134:137], v[26:29]
	v_mfma_f32_16x16x32_bf16 v[30:33], v[158:161], v[134:137], v[30:33]
	v_mfma_f32_16x16x32_bf16 v[34:37], v[146:149], v[138:141], v[34:37]
	v_mfma_f32_16x16x32_bf16 v[38:41], v[150:153], v[138:141], v[38:41]
	v_mfma_f32_16x16x32_bf16 v[42:45], v[154:157], v[138:141], v[42:45]
	v_mfma_f32_16x16x32_bf16 v[46:49], v[158:161], v[138:141], v[46:49]
	v_mfma_f32_16x16x32_bf16 v[50:53], v[146:149], v[142:145], v[50:53]
	v_mfma_f32_16x16x32_bf16 v[54:57], v[150:153], v[142:145], v[54:57]
	v_mfma_f32_16x16x32_bf16 v[58:61], v[154:157], v[142:145], v[58:61]
	v_mfma_f32_16x16x32_bf16 v[62:65], v[158:161], v[142:145], v[62:65]
	v_mfma_f32_16x16x32_bf16 v[2:5], v[228:231], v[212:215], v[2:5]
	v_mfma_f32_16x16x32_bf16 v[6:9], v[232:235], v[212:215], v[6:9]
	v_mfma_f32_16x16x32_bf16 v[10:13], v[236:239], v[212:215], v[10:13]
	v_mfma_f32_16x16x32_bf16 v[14:17], v[240:243], v[212:215], v[14:17]
	v_mfma_f32_16x16x32_bf16 v[18:21], v[228:231], v[216:219], v[18:21]
	v_mfma_f32_16x16x32_bf16 v[22:25], v[232:235], v[216:219], v[22:25]
	v_mfma_f32_16x16x32_bf16 v[26:29], v[236:239], v[216:219], v[26:29]
	v_mfma_f32_16x16x32_bf16 v[30:33], v[240:243], v[216:219], v[30:33]
	v_mfma_f32_16x16x32_bf16 v[34:37], v[228:231], v[220:223], v[34:37]
	v_mfma_f32_16x16x32_bf16 v[38:41], v[232:235], v[220:223], v[38:41]
	v_mfma_f32_16x16x32_bf16 v[42:45], v[236:239], v[220:223], v[42:45]
	v_mfma_f32_16x16x32_bf16 v[46:49], v[240:243], v[220:223], v[46:49]
	v_mfma_f32_16x16x32_bf16 v[50:53], v[228:231], v[224:227], v[50:53]
	v_mfma_f32_16x16x32_bf16 v[54:57], v[232:235], v[224:227], v[54:57]
	v_mfma_f32_16x16x32_bf16 v[58:61], v[236:239], v[224:227], v[58:61]
	v_mfma_f32_16x16x32_bf16 v[62:65], v[240:243], v[224:227], v[62:65]
	s_barrier
	s_mov_b32 s16, 3
.Lop_kloop2:
	v_add_u32_e32 v204, 0x18000, v200
	v_add_u32_e32 v205, 0x18000, v202
	ds_read_b128 v[130:133], v204 offset:0
	ds_read_b128 v[134:137], v204 offset:2048
	ds_read_b128 v[138:141], v204 offset:4096
	ds_read_b128 v[142:145], v204 offset:6144
	ds_read_b128 v[146:149], v205 offset:0
	ds_read_b128 v[150:153], v205 offset:2048
	ds_read_b128 v[154:157], v205 offset:4096
	ds_read_b128 v[158:161], v205 offset:6144
	v_add_u32_e32 v204, 0x18000, v201
	v_add_u32_e32 v205, 0x18000, v203
	ds_read_b128 v[212:215], v204 offset:0
	ds_read_b128 v[216:219], v204 offset:2048
	ds_read_b128 v[220:223], v204 offset:4096
	ds_read_b128 v[224:227], v204 offset:6144
	ds_read_b128 v[228:231], v205 offset:0
	ds_read_b128 v[232:235], v205 offset:2048
	ds_read_b128 v[236:239], v205 offset:4096
	ds_read_b128 v[240:243], v205 offset:6144
	s_add_u32 m0, s76, 0xc000
	s_nop 0
	global_load_lds_dwordx4 v196, s[68:69]
	s_add_u32 m0, s76, 0xe000
	s_nop 0
	global_load_lds_dwordx4 v197, s[68:69]
	s_add_u32 m0, s76, 0x10000
	s_nop 0
	global_load_lds_dwordx4 v198, s[68:69]
	s_add_u32 m0, s76, 0x12000
	s_nop 0
	global_load_lds_dwordx4 v199, s[68:69]
	s_add_u32 m0, s76, 0x14000
	s_nop 0
	global_load_lds_dwordx4 v196, s[70:71]
	s_add_u32 m0, s76, 0x16000
	s_nop 0
	global_load_lds_dwordx4 v197, s[70:71]
	s_add_u32 s68, s68, 0x80
	s_addc_u32 s69, s69, 0
	s_add_u32 s70, s70, 0x80
	s_addc_u32 s71, s71, 0
	s_waitcnt vmcnt(6)
	s_waitcnt lgkmcnt(0)
	s_barrier
	v_mfma_f32_16x16x32_bf16 v[2:5], v[146:149], v[130:133], v[2:5]
	v_mfma_f32_16x16x32_bf16 v[6:9], v[150:153], v[130:133], v[6:9]
	v_mfma_f32_16x16x32_bf16 v[10:13], v[154:157], v[130:133], v[10:13]
	v_mfma_f32_16x16x32_bf16 v[14:17], v[158:161], v[130:133], v[14:17]
	v_mfma_f32_16x16x32_bf16 v[18:21], v[146:149], v[134:137], v[18:21]
	v_mfma_f32_16x16x32_bf16 v[22:25], v[150:153], v[134:137], v[22:25]
	v_mfma_f32_16x16x32_bf16 v[26:29], v[154:157], v[134:137], v[26:29]
	v_mfma_f32_16x16x32_bf16 v[30:33], v[158:161], v[134:137], v[30:33]
	v_mfma_f32_16x16x32_bf16 v[34:37], v[146:149], v[138:141], v[34:37]
	v_mfma_f32_16x16x32_bf16 v[38:41], v[150:153], v[138:141], v[38:41]
	v_mfma_f32_16x16x32_bf16 v[42:45], v[154:157], v[138:141], v[42:45]
	v_mfma_f32_16x16x32_bf16 v[46:49], v[158:161], v[138:141], v[46:49]
	v_mfma_f32_16x16x32_bf16 v[50:53], v[146:149], v[142:145], v[50:53]
	v_mfma_f32_16x16x32_bf16 v[54:57], v[150:153], v[142:145], v[54:57]
	v_mfma_f32_16x16x32_bf16 v[58:61], v[154:157], v[142:145], v[58:61]
	v_mfma_f32_16x16x32_bf16 v[62:65], v[158:161], v[142:145], v[62:65]
	v_mfma_f32_16x16x32_bf16 v[2:5], v[228:231], v[212:215], v[2:5]
	v_mfma_f32_16x16x32_bf16 v[6:9], v[232:235], v[212:215], v[6:9]
	v_mfma_f32_16x16x32_bf16 v[10:13], v[236:239], v[212:215], v[10:13]
	v_mfma_f32_16x16x32_bf16 v[14:17], v[240:243], v[212:215], v[14:17]
	v_mfma_f32_16x16x32_bf16 v[18:21], v[228:231], v[216:219], v[18:21]
	v_mfma_f32_16x16x32_bf16 v[22:25], v[232:235], v[216:219], v[22:25]
	v_mfma_f32_16x16x32_bf16 v[26:29], v[236:239], v[216:219], v[26:29]
	v_mfma_f32_16x16x32_bf16 v[30:33], v[240:243], v[216:219], v[30:33]
	v_mfma_f32_16x16x32_bf16 v[34:37], v[228:231], v[220:223], v[34:37]
	v_mfma_f32_16x16x32_bf16 v[38:41], v[232:235], v[220:223], v[38:41]
	v_mfma_f32_16x16x32_bf16 v[42:45], v[236:239], v[220:223], v[42:45]
	v_mfma_f32_16x16x32_bf16 v[46:49], v[240:243], v[220:223], v[46:49]
	v_mfma_f32_16x16x32_bf16 v[50:53], v[228:231], v[224:227], v[50:53]
	v_mfma_f32_16x16x32_bf16 v[54:57], v[232:235], v[224:227], v[54:57]
	v_mfma_f32_16x16x32_bf16 v[58:61], v[236:239], v[224:227], v[58:61]
	v_mfma_f32_16x16x32_bf16 v[62:65], v[240:243], v[224:227], v[62:65]
	s_barrier
	v_add_u32_e32 v204, 0x0, v200
	v_add_u32_e32 v205, 0x0, v202
	ds_read_b128 v[130:133], v204 offset:0
	ds_read_b128 v[134:137], v204 offset:2048
	ds_read_b128 v[138:141], v204 offset:4096
	ds_read_b128 v[142:145], v204 offset:6144
	ds_read_b128 v[146:149], v205 offset:0
	ds_read_b128 v[150:153], v205 offset:2048
	ds_read_b128 v[154:157], v205 offset:4096
	ds_read_b128 v[158:161], v205 offset:6144
	v_add_u32_e32 v204, 0x0, v201
	v_add_u32_e32 v205, 0x0, v203
	ds_read_b128 v[212:215], v204 offset:0
	ds_read_b128 v[216:219], v204 offset:2048
	ds_read_b128 v[220:223], v204 offset:4096
	ds_read_b128 v[224:227], v204 offset:6144
	ds_read_b128 v[228:231], v205 offset:0
	ds_read_b128 v[232:235], v205 offset:2048
	ds_read_b128 v[236:239], v205 offset:4096
	ds_read_b128 v[240:243], v205 offset:6144
	s_add_u32 m0, s76, 0x18000
	s_nop 0
	global_load_lds_dwordx4 v196, s[68:69]
	s_add_u32 m0, s76, 0x1a000
	s_nop 0
	global_load_lds_dwordx4 v197, s[68:69]
	s_add_u32 m0, s76, 0x1c000
	s_nop 0
	global_load_lds_dwordx4 v198, s[68:69]
	s_add_u32 m0, s76, 0x1e000
	s_nop 0
	global_load_lds_dwordx4 v199, s[68:69]
	s_add_u32 m0, s76, 0x20000
	s_nop 0
	global_load_lds_dwordx4 v196, s[70:71]
	s_add_u32 m0, s76, 0x22000
	s_nop 0
	global_load_lds_dwordx4 v197, s[70:71]
	s_add_u32 s68, s68, 0x80
	s_addc_u32 s69, s69, 0
	s_add_u32 s70, s70, 0x80
	s_addc_u32 s71, s71, 0
	s_waitcnt vmcnt(6)
	s_waitcnt lgkmcnt(0)
	s_barrier
	v_mfma_f32_16x16x32_bf16 v[2:5], v[146:149], v[130:133], v[2:5]
	v_mfma_f32_16x16x32_bf16 v[6:9], v[150:153], v[130:133], v[6:9]
	v_mfma_f32_16x16x32_bf16 v[10:13], v[154:157], v[130:133], v[10:13]
	v_mfma_f32_16x16x32_bf16 v[14:17], v[158:161], v[130:133], v[14:17]
	v_mfma_f32_16x16x32_bf16 v[18:21], v[146:149], v[134:137], v[18:21]
	v_mfma_f32_16x16x32_bf16 v[22:25], v[150:153], v[134:137], v[22:25]
	v_mfma_f32_16x16x32_bf16 v[26:29], v[154:157], v[134:137], v[26:29]
	v_mfma_f32_16x16x32_bf16 v[30:33], v[158:161], v[134:137], v[30:33]
	v_mfma_f32_16x16x32_bf16 v[34:37], v[146:149], v[138:141], v[34:37]
	v_mfma_f32_16x16x32_bf16 v[38:41], v[150:153], v[138:141], v[38:41]
	v_mfma_f32_16x16x32_bf16 v[42:45], v[154:157], v[138:141], v[42:45]
	v_mfma_f32_16x16x32_bf16 v[46:49], v[158:161], v[138:141], v[46:49]
	v_mfma_f32_16x16x32_bf16 v[50:53], v[146:149], v[142:145], v[50:53]
	v_mfma_f32_16x16x32_bf16 v[54:57], v[150:153], v[142:145], v[54:57]
	v_mfma_f32_16x16x32_bf16 v[58:61], v[154:157], v[142:145], v[58:61]
	v_mfma_f32_16x16x32_bf16 v[62:65], v[158:161], v[142:145], v[62:65]
	v_mfma_f32_16x16x32_bf16 v[2:5], v[228:231], v[212:215], v[2:5]
	v_mfma_f32_16x16x32_bf16 v[6:9], v[232:235], v[212:215], v[6:9]
	v_mfma_f32_16x16x32_bf16 v[10:13], v[236:239], v[212:215], v[10:13]
	v_mfma_f32_16x16x32_bf16 v[14:17], v[240:243], v[212:215], v[14:17]
	v_mfma_f32_16x16x32_bf16 v[18:21], v[228:231], v[216:219], v[18:21]
	v_mfma_f32_16x16x32_bf16 v[22:25], v[232:235], v[216:219], v[22:25]
	v_mfma_f32_16x16x32_bf16 v[26:29], v[236:239], v[216:219], v[26:29]
	v_mfma_f32_16x16x32_bf16 v[30:33], v[240:243], v[216:219], v[30:33]
	v_mfma_f32_16x16x32_bf16 v[34:37], v[228:231], v[220:223], v[34:37]
	v_mfma_f32_16x16x32_bf16 v[38:41], v[232:235], v[220:223], v[38:41]
	v_mfma_f32_16x16x32_bf16 v[42:45], v[236:239], v[220:223], v[42:45]
	v_mfma_f32_16x16x32_bf16 v[46:49], v[240:243], v[220:223], v[46:49]
	v_mfma_f32_16x16x32_bf16 v[50:53], v[228:231], v[224:227], v[50:53]
	v_mfma_f32_16x16x32_bf16 v[54:57], v[232:235], v[224:227], v[54:57]
	v_mfma_f32_16x16x32_bf16 v[58:61], v[236:239], v[224:227], v[58:61]
	v_mfma_f32_16x16x32_bf16 v[62:65], v[240:243], v[224:227], v[62:65]
	s_barrier
	v_add_u32_e32 v204, 0xc000, v200
	v_add_u32_e32 v205, 0xc000, v202
	ds_read_b128 v[130:133], v204 offset:0
	ds_read_b128 v[134:137], v204 offset:2048
	ds_read_b128 v[138:141], v204 offset:4096
	ds_read_b128 v[142:145], v204 offset:6144
	ds_read_b128 v[146:149], v205 offset:0
	ds_read_b128 v[150:153], v205 offset:2048
	ds_read_b128 v[154:157], v205 offset:4096
	ds_read_b128 v[158:161], v205 offset:6144
	v_add_u32_e32 v204, 0xc000, v201
	v_add_u32_e32 v205, 0xc000, v203
	ds_read_b128 v[212:215], v204 offset:0
	ds_read_b128 v[216:219], v204 offset:2048
	ds_read_b128 v[220:223], v204 offset:4096
	ds_read_b128 v[224:227], v204 offset:6144
	ds_read_b128 v[228:231], v205 offset:0
	ds_read_b128 v[232:235], v205 offset:2048
	ds_read_b128 v[236:239], v205 offset:4096
	ds_read_b128 v[240:243], v205 offset:6144
	s_add_u32 m0, s76, 0x0
	s_nop 0
	global_load_lds_dwordx4 v196, s[68:69]
	s_add_u32 m0, s76, 0x2000
	s_nop 0
	global_load_lds_dwordx4 v197, s[68:69]
	s_add_u32 m0, s76, 0x4000
	s_nop 0
	global_load_lds_dwordx4 v198, s[68:69]
	s_add_u32 m0, s76, 0x6000
	s_nop 0
	global_load_lds_dwordx4 v199, s[68:69]
	s_add_u32 m0, s76, 0x8000
	s_nop 0
	global_load_lds_dwordx4 v196, s[70:71]
	s_add_u32 m0, s76, 0xa000
	s_nop 0
	global_load_lds_dwordx4 v197, s[70:71]
	s_add_u32 s68, s68, 0x80
	s_addc_u32 s69, s69, 0
	s_add_u32 s70, s70, 0x80
	s_addc_u32 s71, s71, 0
	s_waitcnt vmcnt(6)
	s_waitcnt lgkmcnt(0)
	s_barrier
	v_mfma_f32_16x16x32_bf16 v[2:5], v[146:149], v[130:133], v[2:5]
	v_mfma_f32_16x16x32_bf16 v[6:9], v[150:153], v[130:133], v[6:9]
	v_mfma_f32_16x16x32_bf16 v[10:13], v[154:157], v[130:133], v[10:13]
	v_mfma_f32_16x16x32_bf16 v[14:17], v[158:161], v[130:133], v[14:17]
	v_mfma_f32_16x16x32_bf16 v[18:21], v[146:149], v[134:137], v[18:21]
	v_mfma_f32_16x16x32_bf16 v[22:25], v[150:153], v[134:137], v[22:25]
	v_mfma_f32_16x16x32_bf16 v[26:29], v[154:157], v[134:137], v[26:29]
	v_mfma_f32_16x16x32_bf16 v[30:33], v[158:161], v[134:137], v[30:33]
	v_mfma_f32_16x16x32_bf16 v[34:37], v[146:149], v[138:141], v[34:37]
	v_mfma_f32_16x16x32_bf16 v[38:41], v[150:153], v[138:141], v[38:41]
	v_mfma_f32_16x16x32_bf16 v[42:45], v[154:157], v[138:141], v[42:45]
	v_mfma_f32_16x16x32_bf16 v[46:49], v[158:161], v[138:141], v[46:49]
	v_mfma_f32_16x16x32_bf16 v[50:53], v[146:149], v[142:145], v[50:53]
	v_mfma_f32_16x16x32_bf16 v[54:57], v[150:153], v[142:145], v[54:57]
	v_mfma_f32_16x16x32_bf16 v[58:61], v[154:157], v[142:145], v[58:61]
	v_mfma_f32_16x16x32_bf16 v[62:65], v[158:161], v[142:145], v[62:65]
	v_mfma_f32_16x16x32_bf16 v[2:5], v[228:231], v[212:215], v[2:5]
	v_mfma_f32_16x16x32_bf16 v[6:9], v[232:235], v[212:215], v[6:9]
	v_mfma_f32_16x16x32_bf16 v[10:13], v[236:239], v[212:215], v[10:13]
	v_mfma_f32_16x16x32_bf16 v[14:17], v[240:243], v[212:215], v[14:17]
	v_mfma_f32_16x16x32_bf16 v[18:21], v[228:231], v[216:219], v[18:21]
	v_mfma_f32_16x16x32_bf16 v[22:25], v[232:235], v[216:219], v[22:25]
	v_mfma_f32_16x16x32_bf16 v[26:29], v[236:239], v[216:219], v[26:29]
	v_mfma_f32_16x16x32_bf16 v[30:33], v[240:243], v[216:219], v[30:33]
	v_mfma_f32_16x16x32_bf16 v[34:37], v[228:231], v[220:223], v[34:37]
	v_mfma_f32_16x16x32_bf16 v[38:41], v[232:235], v[220:223], v[38:41]
	v_mfma_f32_16x16x32_bf16 v[42:45], v[236:239], v[220:223], v[42:45]
	v_mfma_f32_16x16x32_bf16 v[46:49], v[240:243], v[220:223], v[46:49]
	v_mfma_f32_16x16x32_bf16 v[50:53], v[228:231], v[224:227], v[50:53]
	v_mfma_f32_16x16x32_bf16 v[54:57], v[232:235], v[224:227], v[54:57]
	v_mfma_f32_16x16x32_bf16 v[58:61], v[236:239], v[224:227], v[58:61]
	v_mfma_f32_16x16x32_bf16 v[62:65], v[240:243], v[224:227], v[62:65]
	s_barrier
	s_add_i32 s16, s16, -1
	s_cmp_lg_u32 s16, 0
	s_cbranch_scc1 .Lop_kloop2
	v_add_u32_e32 v204, 0x18000, v200
	v_add_u32_e32 v205, 0x18000, v202
	ds_read_b128 v[130:133], v204 offset:0
	ds_read_b128 v[134:137], v204 offset:2048
	ds_read_b128 v[138:141], v204 offset:4096
	ds_read_b128 v[142:145], v204 offset:6144
	ds_read_b128 v[146:149], v205 offset:0
	ds_read_b128 v[150:153], v205 offset:2048
	ds_read_b128 v[154:157], v205 offset:4096
	ds_read_b128 v[158:161], v205 offset:6144
	v_add_u32_e32 v204, 0x18000, v201
	v_add_u32_e32 v205, 0x18000, v203
	ds_read_b128 v[212:215], v204 offset:0
	ds_read_b128 v[216:219], v204 offset:2048
	ds_read_b128 v[220:223], v204 offset:4096
	ds_read_b128 v[224:227], v204 offset:6144
	ds_read_b128 v[228:231], v205 offset:0
	ds_read_b128 v[232:235], v205 offset:2048
	ds_read_b128 v[236:239], v205 offset:4096
	ds_read_b128 v[240:243], v205 offset:6144
	s_waitcnt vmcnt(0)
	s_waitcnt lgkmcnt(0)
	s_barrier
	v_mfma_f32_16x16x32_bf16 v[2:5], v[146:149], v[130:133], v[2:5]
	v_mfma_f32_16x16x32_bf16 v[6:9], v[150:153], v[130:133], v[6:9]
	v_mfma_f32_16x16x32_bf16 v[10:13], v[154:157], v[130:133], v[10:13]
	v_mfma_f32_16x16x32_bf16 v[14:17], v[158:161], v[130:133], v[14:17]
	v_mfma_f32_16x16x32_bf16 v[18:21], v[146:149], v[134:137], v[18:21]
	v_mfma_f32_16x16x32_bf16 v[22:25], v[150:153], v[134:137], v[22:25]
	v_mfma_f32_16x16x32_bf16 v[26:29], v[154:157], v[134:137], v[26:29]
	v_mfma_f32_16x16x32_bf16 v[30:33], v[158:161], v[134:137], v[30:33]
	v_mfma_f32_16x16x32_bf16 v[34:37], v[146:149], v[138:141], v[34:37]
	v_mfma_f32_16x16x32_bf16 v[38:41], v[150:153], v[138:141], v[38:41]
	v_mfma_f32_16x16x32_bf16 v[42:45], v[154:157], v[138:141], v[42:45]
	v_mfma_f32_16x16x32_bf16 v[46:49], v[158:161], v[138:141], v[46:49]
	v_mfma_f32_16x16x32_bf16 v[50:53], v[146:149], v[142:145], v[50:53]
	v_mfma_f32_16x16x32_bf16 v[54:57], v[150:153], v[142:145], v[54:57]
	v_mfma_f32_16x16x32_bf16 v[58:61], v[154:157], v[142:145], v[58:61]
	v_mfma_f32_16x16x32_bf16 v[62:65], v[158:161], v[142:145], v[62:65]
	v_mfma_f32_16x16x32_bf16 v[2:5], v[228:231], v[212:215], v[2:5]
	v_mfma_f32_16x16x32_bf16 v[6:9], v[232:235], v[212:215], v[6:9]
	v_mfma_f32_16x16x32_bf16 v[10:13], v[236:239], v[212:215], v[10:13]
	v_mfma_f32_16x16x32_bf16 v[14:17], v[240:243], v[212:215], v[14:17]
	v_mfma_f32_16x16x32_bf16 v[18:21], v[228:231], v[216:219], v[18:21]
	v_mfma_f32_16x16x32_bf16 v[22:25], v[232:235], v[216:219], v[22:25]
	v_mfma_f32_16x16x32_bf16 v[26:29], v[236:239], v[216:219], v[26:29]
	v_mfma_f32_16x16x32_bf16 v[30:33], v[240:243], v[216:219], v[30:33]
	v_mfma_f32_16x16x32_bf16 v[34:37], v[228:231], v[220:223], v[34:37]
	v_mfma_f32_16x16x32_bf16 v[38:41], v[232:235], v[220:223], v[38:41]
	v_mfma_f32_16x16x32_bf16 v[42:45], v[236:239], v[220:223], v[42:45]
	v_mfma_f32_16x16x32_bf16 v[46:49], v[240:243], v[220:223], v[46:49]
	v_mfma_f32_16x16x32_bf16 v[50:53], v[228:231], v[224:227], v[50:53]
	v_mfma_f32_16x16x32_bf16 v[54:57], v[232:235], v[224:227], v[54:57]
	v_mfma_f32_16x16x32_bf16 v[58:61], v[236:239], v[224:227], v[58:61]
	v_mfma_f32_16x16x32_bf16 v[62:65], v[240:243], v[224:227], v[62:65]
	s_barrier
	v_add_u32_e32 v204, 0x0, v200
	v_add_u32_e32 v205, 0x0, v202
	ds_read_b128 v[130:133], v204 offset:0
	ds_read_b128 v[134:137], v204 offset:2048
	ds_read_b128 v[138:141], v204 offset:4096
	ds_read_b128 v[142:145], v204 offset:6144
	ds_read_b128 v[146:149], v205 offset:0
	ds_read_b128 v[150:153], v205 offset:2048
	ds_read_b128 v[154:157], v205 offset:4096
	ds_read_b128 v[158:161], v205 offset:6144
	v_add_u32_e32 v204, 0x0, v201
	v_add_u32_e32 v205, 0x0, v203
	ds_read_b128 v[212:215], v204 offset:0
	ds_read_b128 v[216:219], v204 offset:2048
	ds_read_b128 v[220:223], v204 offset:4096
	ds_read_b128 v[224:227], v204 offset:6144
	ds_read_b128 v[228:231], v205 offset:0
	ds_read_b128 v[232:235], v205 offset:2048
	ds_read_b128 v[236:239], v205 offset:4096
	ds_read_b128 v[240:243], v205 offset:6144
	s_waitcnt lgkmcnt(0)
	s_barrier
	v_mfma_f32_16x16x32_bf16 v[2:5], v[146:149], v[130:133], v[2:5]
	v_mfma_f32_16x16x32_bf16 v[6:9], v[150:153], v[130:133], v[6:9]
	v_mfma_f32_16x16x32_bf16 v[10:13], v[154:157], v[130:133], v[10:13]
	v_mfma_f32_16x16x32_bf16 v[14:17], v[158:161], v[130:133], v[14:17]
	v_mfma_f32_16x16x32_bf16 v[18:21], v[146:149], v[134:137], v[18:21]
	v_mfma_f32_16x16x32_bf16 v[22:25], v[150:153], v[134:137], v[22:25]
	v_mfma_f32_16x16x32_bf16 v[26:29], v[154:157], v[134:137], v[26:29]
	v_mfma_f32_16x16x32_bf16 v[30:33], v[158:161], v[134:137], v[30:33]
	v_mfma_f32_16x16x32_bf16 v[34:37], v[146:149], v[138:141], v[34:37]
	v_mfma_f32_16x16x32_bf16 v[38:41], v[150:153], v[138:141], v[38:41]
	v_mfma_f32_16x16x32_bf16 v[42:45], v[154:157], v[138:141], v[42:45]
	v_mfma_f32_16x16x32_bf16 v[46:49], v[158:161], v[138:141], v[46:49]
	v_mfma_f32_16x16x32_bf16 v[50:53], v[146:149], v[142:145], v[50:53]
	v_mfma_f32_16x16x32_bf16 v[54:57], v[150:153], v[142:145], v[54:57]
	v_mfma_f32_16x16x32_bf16 v[58:61], v[154:157], v[142:145], v[58:61]
	v_mfma_f32_16x16x32_bf16 v[62:65], v[158:161], v[142:145], v[62:65]
	v_mfma_f32_16x16x32_bf16 v[2:5], v[228:231], v[212:215], v[2:5]
	v_mfma_f32_16x16x32_bf16 v[6:9], v[232:235], v[212:215], v[6:9]
	v_mfma_f32_16x16x32_bf16 v[10:13], v[236:239], v[212:215], v[10:13]
	v_mfma_f32_16x16x32_bf16 v[14:17], v[240:243], v[212:215], v[14:17]
	v_mfma_f32_16x16x32_bf16 v[18:21], v[228:231], v[216:219], v[18:21]
	v_mfma_f32_16x16x32_bf16 v[22:25], v[232:235], v[216:219], v[22:25]
	v_mfma_f32_16x16x32_bf16 v[26:29], v[236:239], v[216:219], v[26:29]
	v_mfma_f32_16x16x32_bf16 v[30:33], v[240:243], v[216:219], v[30:33]
	v_mfma_f32_16x16x32_bf16 v[34:37], v[228:231], v[220:223], v[34:37]
	v_mfma_f32_16x16x32_bf16 v[38:41], v[232:235], v[220:223], v[38:41]
	v_mfma_f32_16x16x32_bf16 v[42:45], v[236:239], v[220:223], v[42:45]
	v_mfma_f32_16x16x32_bf16 v[46:49], v[240:243], v[220:223], v[46:49]
	v_mfma_f32_16x16x32_bf16 v[50:53], v[228:231], v[224:227], v[50:53]
	v_mfma_f32_16x16x32_bf16 v[54:57], v[232:235], v[224:227], v[54:57]
	v_mfma_f32_16x16x32_bf16 v[58:61], v[236:239], v[224:227], v[58:61]
	v_mfma_f32_16x16x32_bf16 v[62:65], v[240:243], v[224:227], v[62:65]
